# v83: transposed tile write (transposing norm and gMLP transpose): 8 lanes complete one 128-byte line of a channel instead of 64 scattered 16-byte pieces; LDS tile rows padded to 2056 B
# speedup vs baseline: 1.0009x; 1.0009x over previous
.LBB0_9:
	s_mul_i32 s3, s6, 3
	s_getpc_b64 s[0:1]
	s_add_u32 s0, s0, PROG@rel32@lo+4
	s_addc_u32 s1, s1, PROG@rel32@hi+12
	s_and_b32 s2, s3, -4
	s_add_u32 s0, s0, s2
	s_addc_u32 s1, s1, 0
	s_load_dwordx2 s[0:1], s[0:1], 0x0
	s_and_b32 s3, s3, 3
	s_lshl_b32 s3, s3, 3
	s_waitcnt lgkmcnt(0)
	s_lshr_b64 s[0:1], s[0:1], s3
	s_and_b32 s2, s0, 0xffff
	v_mov_b32_e32 v0, s2
	s_bfe_u32 s2, s0, 0x80010
	v_mov_b32_e32 v2, s2
	s_cmp_gt_u32 s6, 1
	s_cbranch_scc1 .Lsm_done
	v_readlane_b32 s0, v254, 39
	v_readlane_b32 s1, v254, 40
	s_add_u32 s0, s0, 0xc000
	s_addc_u32 s1, s1, 0
	s_cmp_eq_u32 s6, 1
	s_cbranch_scc1 .Lsm_cache
	s_getreg_b32 s2, hwreg(HW_REG_XCC_ID, 0, 4)
	s_and_b32 s2, s2, 15
	s_lshl_b32 s2, 1, s2
	s_and_b32 s3, s66, 7
	s_lshl_b32 s3, s3, 2
	s_add_u32 s0, s0, s3
	s_addc_u32 s1, s1, 0
	v_mov_b32_e32 v3, s2
	s_mov_b64 s[2:3], exec
	s_mov_b64 exec, 1
	global_atomic_or v1, v3, s[0:1]
	s_mov_b64 exec, s[2:3]
	s_branch .Lsm_done
	s_nop 0
	s_nop 0
	s_nop 0
	s_nop 0
	s_nop 0
	s_nop 0
	s_nop 0
	s_nop 0
	s_nop 0
	s_nop 0
	s_nop 0
	s_nop 0
	s_nop 0
	s_nop 0

.LBB0_119:
	s_ashr_i32 s7, s6, 31
	s_lshl_b64 s[8:9], s[6:7], 11
	v_lshl_add_u64 v[8:9], v[6:7], 0, s[8:9]
	s_mov_b64 s[8:9], 0
	v_mov_b32_e32 v10, v50
	v_readlane_b32 s9, v254, 63
	s_mul_i32 s9, s9, 64
	v_add_u32_e32 v10, s9, v10
	v_add_co_u32_e32 v80, vcc, 0xe800000, v8
	s_nop 1
	v_addc_co_u32_e32 v81, vcc, 0, v9, vcc
	global_load_dwordx2 v[84:85], v[80:81], off
	global_load_dwordx2 v[86:87], v[80:81], off offset:512
	global_load_dwordx2 v[88:89], v[80:81], off offset:1024
	global_load_dwordx2 v[90:91], v[80:81], off offset:1536
	global_load_dwordx2 v[92:93], v[80:81], off offset:2048
	global_load_dwordx2 v[94:95], v[80:81], off offset:2560
	global_load_dwordx2 v[96:97], v[80:81], off offset:3072
	global_load_dwordx2 v[98:99], v[80:81], off offset:3584
	v_add_co_u32_e32 v80, vcc, 0x1000, v80
	s_nop 1
	v_addc_co_u32_e32 v81, vcc, 0, v81, vcc
	global_load_dwordx2 v[100:101], v[80:81], off
	global_load_dwordx2 v[102:103], v[80:81], off offset:512
	global_load_dwordx2 v[104:105], v[80:81], off offset:1024
	global_load_dwordx2 v[106:107], v[80:81], off offset:1536
	global_load_dwordx2 v[108:109], v[80:81], off offset:2048
	global_load_dwordx2 v[110:111], v[80:81], off offset:2560
	global_load_dwordx2 v[112:113], v[80:81], off offset:3072
	global_load_dwordx2 v[114:115], v[80:81], off offset:3584
	v_add_co_u32_e32 v80, vcc, 0x1000, v80
	s_nop 1
	v_addc_co_u32_e32 v81, vcc, 0, v81, vcc
	global_load_dwordx2 v[116:117], v[80:81], off
	global_load_dwordx2 v[118:119], v[80:81], off offset:512
	global_load_dwordx2 v[120:121], v[80:81], off offset:1024
	global_load_dwordx2 v[122:123], v[80:81], off offset:1536
	global_load_dwordx2 v[124:125], v[80:81], off offset:2048
	global_load_dwordx2 v[126:127], v[80:81], off offset:2560
	global_load_dwordx2 v[128:129], v[80:81], off offset:3072
	global_load_dwordx2 v[130:131], v[80:81], off offset:3584
	v_add_co_u32_e32 v80, vcc, 0x1000, v80
	s_nop 1
	v_addc_co_u32_e32 v81, vcc, 0, v81, vcc
	global_load_dwordx2 v[132:133], v[80:81], off
	global_load_dwordx2 v[134:135], v[80:81], off offset:512
	global_load_dwordx2 v[136:137], v[80:81], off offset:1024
	global_load_dwordx2 v[138:139], v[80:81], off offset:1536
	global_load_dwordx2 v[140:141], v[80:81], off offset:2048
	global_load_dwordx2 v[142:143], v[80:81], off offset:2560
	global_load_dwordx2 v[144:145], v[80:81], off offset:3072
	global_load_dwordx2 v[146:147], v[80:81], off offset:3584
	s_mov_b32 s8, 0x3a800000
	s_waitcnt vmcnt(28)
	v_lshlrev_b32_e32 v82, 16, v84
	v_and_b32_e32 v83, 0xffff0000, v84
	v_mul_f32_e32 v148, v82, v82
	v_fmac_f32_e32 v148, v83, v83
	v_lshlrev_b32_e32 v82, 16, v85
	v_and_b32_e32 v83, 0xffff0000, v85
	v_fmac_f32_e32 v148, v82, v82
	v_fmac_f32_e32 v148, v83, v83
	v_lshlrev_b32_e32 v82, 16, v86
	v_and_b32_e32 v83, 0xffff0000, v86
	v_fmac_f32_e32 v148, v82, v82
	v_fmac_f32_e32 v148, v83, v83
	v_lshlrev_b32_e32 v82, 16, v87
	v_and_b32_e32 v83, 0xffff0000, v87
	v_fmac_f32_e32 v148, v82, v82
	v_fmac_f32_e32 v148, v83, v83
	v_lshlrev_b32_e32 v82, 16, v88
	v_and_b32_e32 v83, 0xffff0000, v88
	v_fmac_f32_e32 v148, v82, v82
	v_fmac_f32_e32 v148, v83, v83
	v_lshlrev_b32_e32 v82, 16, v89
	v_and_b32_e32 v83, 0xffff0000, v89
	v_fmac_f32_e32 v148, v82, v82
	v_fmac_f32_e32 v148, v83, v83
	v_lshlrev_b32_e32 v82, 16, v90
	v_and_b32_e32 v83, 0xffff0000, v90
	v_fmac_f32_e32 v148, v82, v82
	v_fmac_f32_e32 v148, v83, v83
	v_lshlrev_b32_e32 v82, 16, v91
	v_and_b32_e32 v83, 0xffff0000, v91
	v_fmac_f32_e32 v148, v82, v82
	v_fmac_f32_e32 v148, v83, v83
	s_waitcnt vmcnt(24)
	v_lshlrev_b32_e32 v82, 16, v92
	v_and_b32_e32 v83, 0xffff0000, v92
	v_mul_f32_e32 v149, v82, v82
	v_fmac_f32_e32 v149, v83, v83
	v_lshlrev_b32_e32 v82, 16, v93
	v_and_b32_e32 v83, 0xffff0000, v93
	v_fmac_f32_e32 v149, v82, v82
	v_fmac_f32_e32 v149, v83, v83
	v_lshlrev_b32_e32 v82, 16, v94
	v_and_b32_e32 v83, 0xffff0000, v94
	v_fmac_f32_e32 v149, v82, v82
	v_fmac_f32_e32 v149, v83, v83
	v_lshlrev_b32_e32 v82, 16, v95
	v_and_b32_e32 v83, 0xffff0000, v95
	v_fmac_f32_e32 v149, v82, v82
	v_fmac_f32_e32 v149, v83, v83
	v_lshlrev_b32_e32 v82, 16, v96
	v_and_b32_e32 v83, 0xffff0000, v96
	v_fmac_f32_e32 v149, v82, v82
	v_fmac_f32_e32 v149, v83, v83
	v_lshlrev_b32_e32 v82, 16, v97
	v_and_b32_e32 v83, 0xffff0000, v97
	v_fmac_f32_e32 v149, v82, v82
	v_fmac_f32_e32 v149, v83, v83
	v_lshlrev_b32_e32 v82, 16, v98
	v_and_b32_e32 v83, 0xffff0000, v98
	v_fmac_f32_e32 v149, v82, v82
	v_fmac_f32_e32 v149, v83, v83
	v_lshlrev_b32_e32 v82, 16, v99
	v_and_b32_e32 v83, 0xffff0000, v99
	v_fmac_f32_e32 v149, v82, v82
	v_fmac_f32_e32 v149, v83, v83
	s_waitcnt vmcnt(20)
	v_lshlrev_b32_e32 v82, 16, v100
	v_and_b32_e32 v83, 0xffff0000, v100
	v_mul_f32_e32 v150, v82, v82
	v_fmac_f32_e32 v150, v83, v83
	v_lshlrev_b32_e32 v82, 16, v101
	v_and_b32_e32 v83, 0xffff0000, v101
	v_fmac_f32_e32 v150, v82, v82
	v_fmac_f32_e32 v150, v83, v83
	v_lshlrev_b32_e32 v82, 16, v102
	v_and_b32_e32 v83, 0xffff0000, v102
	v_fmac_f32_e32 v150, v82, v82
	v_fmac_f32_e32 v150, v83, v83
	v_lshlrev_b32_e32 v82, 16, v103
	v_and_b32_e32 v83, 0xffff0000, v103
	v_fmac_f32_e32 v150, v82, v82
	v_fmac_f32_e32 v150, v83, v83
	v_lshlrev_b32_e32 v82, 16, v104
	v_and_b32_e32 v83, 0xffff0000, v104
	v_fmac_f32_e32 v150, v82, v82
	v_fmac_f32_e32 v150, v83, v83
	v_lshlrev_b32_e32 v82, 16, v105
	v_and_b32_e32 v83, 0xffff0000, v105
	v_fmac_f32_e32 v150, v82, v82
	v_fmac_f32_e32 v150, v83, v83
	v_lshlrev_b32_e32 v82, 16, v106
	v_and_b32_e32 v83, 0xffff0000, v106
	v_fmac_f32_e32 v150, v82, v82
	v_fmac_f32_e32 v150, v83, v83
	v_lshlrev_b32_e32 v82, 16, v107
	v_and_b32_e32 v83, 0xffff0000, v107
	v_fmac_f32_e32 v150, v82, v82
	v_fmac_f32_e32 v150, v83, v83
	s_waitcnt vmcnt(16)
	v_lshlrev_b32_e32 v82, 16, v108
	v_and_b32_e32 v83, 0xffff0000, v108
	v_mul_f32_e32 v151, v82, v82
	v_fmac_f32_e32 v151, v83, v83
	v_lshlrev_b32_e32 v82, 16, v109
	v_and_b32_e32 v83, 0xffff0000, v109
	v_fmac_f32_e32 v151, v82, v82
	v_fmac_f32_e32 v151, v83, v83
	v_lshlrev_b32_e32 v82, 16, v110
	v_and_b32_e32 v83, 0xffff0000, v110
	v_fmac_f32_e32 v151, v82, v82
	v_fmac_f32_e32 v151, v83, v83
	v_lshlrev_b32_e32 v82, 16, v111
	v_and_b32_e32 v83, 0xffff0000, v111
	v_fmac_f32_e32 v151, v82, v82
	v_fmac_f32_e32 v151, v83, v83
	v_lshlrev_b32_e32 v82, 16, v112
	v_and_b32_e32 v83, 0xffff0000, v112
	v_fmac_f32_e32 v151, v82, v82
	v_fmac_f32_e32 v151, v83, v83
	v_lshlrev_b32_e32 v82, 16, v113
	v_and_b32_e32 v83, 0xffff0000, v113
	v_fmac_f32_e32 v151, v82, v82
	v_fmac_f32_e32 v151, v83, v83
	v_lshlrev_b32_e32 v82, 16, v114
	v_and_b32_e32 v83, 0xffff0000, v114
	v_fmac_f32_e32 v151, v82, v82
	v_fmac_f32_e32 v151, v83, v83
	v_lshlrev_b32_e32 v82, 16, v115
	v_and_b32_e32 v83, 0xffff0000, v115
	v_fmac_f32_e32 v151, v82, v82
	v_fmac_f32_e32 v151, v83, v83
	s_waitcnt vmcnt(12)
	v_lshlrev_b32_e32 v82, 16, v116
	v_and_b32_e32 v83, 0xffff0000, v116
	v_mul_f32_e32 v152, v82, v82
	v_fmac_f32_e32 v152, v83, v83
	v_lshlrev_b32_e32 v82, 16, v117
	v_and_b32_e32 v83, 0xffff0000, v117
	v_fmac_f32_e32 v152, v82, v82
	v_fmac_f32_e32 v152, v83, v83
	v_lshlrev_b32_e32 v82, 16, v118
	v_and_b32_e32 v83, 0xffff0000, v118
	v_fmac_f32_e32 v152, v82, v82
	v_fmac_f32_e32 v152, v83, v83
	v_lshlrev_b32_e32 v82, 16, v119
	v_and_b32_e32 v83, 0xffff0000, v119
	v_fmac_f32_e32 v152, v82, v82
	v_fmac_f32_e32 v152, v83, v83
	v_lshlrev_b32_e32 v82, 16, v120
	v_and_b32_e32 v83, 0xffff0000, v120
	v_fmac_f32_e32 v152, v82, v82
	v_fmac_f32_e32 v152, v83, v83
	v_lshlrev_b32_e32 v82, 16, v121
	v_and_b32_e32 v83, 0xffff0000, v121
	v_fmac_f32_e32 v152, v82, v82
	v_fmac_f32_e32 v152, v83, v83
	v_lshlrev_b32_e32 v82, 16, v122
	v_and_b32_e32 v83, 0xffff0000, v122
	v_fmac_f32_e32 v152, v82, v82
	v_fmac_f32_e32 v152, v83, v83
	v_lshlrev_b32_e32 v82, 16, v123
	v_and_b32_e32 v83, 0xffff0000, v123
	v_fmac_f32_e32 v152, v82, v82
	v_fmac_f32_e32 v152, v83, v83
	s_waitcnt vmcnt(8)
	v_lshlrev_b32_e32 v82, 16, v124
	v_and_b32_e32 v83, 0xffff0000, v124
	v_mul_f32_e32 v153, v82, v82
	v_fmac_f32_e32 v153, v83, v83
	v_lshlrev_b32_e32 v82, 16, v125
	v_and_b32_e32 v83, 0xffff0000, v125
	v_fmac_f32_e32 v153, v82, v82
	v_fmac_f32_e32 v153, v83, v83
	v_lshlrev_b32_e32 v82, 16, v126
	v_and_b32_e32 v83, 0xffff0000, v126
	v_fmac_f32_e32 v153, v82, v82
	v_fmac_f32_e32 v153, v83, v83
	v_lshlrev_b32_e32 v82, 16, v127
	v_and_b32_e32 v83, 0xffff0000, v127
	v_fmac_f32_e32 v153, v82, v82
	v_fmac_f32_e32 v153, v83, v83
	v_lshlrev_b32_e32 v82, 16, v128
	v_and_b32_e32 v83, 0xffff0000, v128
	v_fmac_f32_e32 v153, v82, v82
	v_fmac_f32_e32 v153, v83, v83
	v_lshlrev_b32_e32 v82, 16, v129
	v_and_b32_e32 v83, 0xffff0000, v129
	v_fmac_f32_e32 v153, v82, v82
	v_fmac_f32_e32 v153, v83, v83
	v_lshlrev_b32_e32 v82, 16, v130
	v_and_b32_e32 v83, 0xffff0000, v130
	v_fmac_f32_e32 v153, v82, v82
	v_fmac_f32_e32 v153, v83, v83
	v_lshlrev_b32_e32 v82, 16, v131
	v_and_b32_e32 v83, 0xffff0000, v131
	v_fmac_f32_e32 v153, v82, v82
	v_fmac_f32_e32 v153, v83, v83
	s_waitcnt vmcnt(4)
	v_lshlrev_b32_e32 v82, 16, v132
	v_and_b32_e32 v83, 0xffff0000, v132
	v_mul_f32_e32 v154, v82, v82
	v_fmac_f32_e32 v154, v83, v83
	v_lshlrev_b32_e32 v82, 16, v133
	v_and_b32_e32 v83, 0xffff0000, v133
	v_fmac_f32_e32 v154, v82, v82
	v_fmac_f32_e32 v154, v83, v83
	v_lshlrev_b32_e32 v82, 16, v134
	v_and_b32_e32 v83, 0xffff0000, v134
	v_fmac_f32_e32 v154, v82, v82
	v_fmac_f32_e32 v154, v83, v83
	v_lshlrev_b32_e32 v82, 16, v135
	v_and_b32_e32 v83, 0xffff0000, v135
	v_fmac_f32_e32 v154, v82, v82
	v_fmac_f32_e32 v154, v83, v83
	v_lshlrev_b32_e32 v82, 16, v136
	v_and_b32_e32 v83, 0xffff0000, v136
	v_fmac_f32_e32 v154, v82, v82
	v_fmac_f32_e32 v154, v83, v83
	v_lshlrev_b32_e32 v82, 16, v137
	v_and_b32_e32 v83, 0xffff0000, v137
	v_fmac_f32_e32 v154, v82, v82
	v_fmac_f32_e32 v154, v83, v83
	v_lshlrev_b32_e32 v82, 16, v138
	v_and_b32_e32 v83, 0xffff0000, v138
	v_fmac_f32_e32 v154, v82, v82
	v_fmac_f32_e32 v154, v83, v83
	v_lshlrev_b32_e32 v82, 16, v139
	v_and_b32_e32 v83, 0xffff0000, v139
	v_fmac_f32_e32 v154, v82, v82
	v_fmac_f32_e32 v154, v83, v83
	s_waitcnt vmcnt(0)
	v_lshlrev_b32_e32 v82, 16, v140
	v_and_b32_e32 v83, 0xffff0000, v140
	v_mul_f32_e32 v155, v82, v82
	v_fmac_f32_e32 v155, v83, v83
	v_lshlrev_b32_e32 v82, 16, v141
	v_and_b32_e32 v83, 0xffff0000, v141
	v_fmac_f32_e32 v155, v82, v82
	v_fmac_f32_e32 v155, v83, v83
	v_lshlrev_b32_e32 v82, 16, v142
	v_and_b32_e32 v83, 0xffff0000, v142
	v_fmac_f32_e32 v155, v82, v82
	v_fmac_f32_e32 v155, v83, v83
	v_lshlrev_b32_e32 v82, 16, v143
	v_and_b32_e32 v83, 0xffff0000, v143
	v_fmac_f32_e32 v155, v82, v82
	v_fmac_f32_e32 v155, v83, v83
	v_lshlrev_b32_e32 v82, 16, v144
	v_and_b32_e32 v83, 0xffff0000, v144
	v_fmac_f32_e32 v155, v82, v82
	v_fmac_f32_e32 v155, v83, v83
	v_lshlrev_b32_e32 v82, 16, v145
	v_and_b32_e32 v83, 0xffff0000, v145
	v_fmac_f32_e32 v155, v82, v82
	v_fmac_f32_e32 v155, v83, v83
	v_lshlrev_b32_e32 v82, 16, v146
	v_and_b32_e32 v83, 0xffff0000, v146
	v_fmac_f32_e32 v155, v82, v82
	v_fmac_f32_e32 v155, v83, v83
	v_lshlrev_b32_e32 v82, 16, v147
	v_and_b32_e32 v83, 0xffff0000, v147
	v_fmac_f32_e32 v155, v82, v82
	v_fmac_f32_e32 v155, v83, v83
	s_nop 1
	v_add_f32_dpp v148, v148, v148 row_ror:8 row_mask:0xf bank_mask:0xf
	v_add_f32_dpp v149, v149, v149 row_ror:8 row_mask:0xf bank_mask:0xf
	v_add_f32_dpp v150, v150, v150 row_ror:8 row_mask:0xf bank_mask:0xf
	v_add_f32_dpp v151, v151, v151 row_ror:8 row_mask:0xf bank_mask:0xf
	v_add_f32_dpp v152, v152, v152 row_ror:8 row_mask:0xf bank_mask:0xf
	v_add_f32_dpp v153, v153, v153 row_ror:8 row_mask:0xf bank_mask:0xf
	v_add_f32_dpp v154, v154, v154 row_ror:8 row_mask:0xf bank_mask:0xf
	v_add_f32_dpp v155, v155, v155 row_ror:8 row_mask:0xf bank_mask:0xf
	v_add_f32_dpp v148, v148, v148 row_ror:4 row_mask:0xf bank_mask:0xf
	v_add_f32_dpp v149, v149, v149 row_ror:4 row_mask:0xf bank_mask:0xf
	v_add_f32_dpp v150, v150, v150 row_ror:4 row_mask:0xf bank_mask:0xf
	v_add_f32_dpp v151, v151, v151 row_ror:4 row_mask:0xf bank_mask:0xf
	v_add_f32_dpp v152, v152, v152 row_ror:4 row_mask:0xf bank_mask:0xf
	v_add_f32_dpp v153, v153, v153 row_ror:4 row_mask:0xf bank_mask:0xf
	v_add_f32_dpp v154, v154, v154 row_ror:4 row_mask:0xf bank_mask:0xf
	v_add_f32_dpp v155, v155, v155 row_ror:4 row_mask:0xf bank_mask:0xf
	v_add_f32_dpp v148, v148, v148 row_ror:2 row_mask:0xf bank_mask:0xf
	v_add_f32_dpp v149, v149, v149 row_ror:2 row_mask:0xf bank_mask:0xf
	v_add_f32_dpp v150, v150, v150 row_ror:2 row_mask:0xf bank_mask:0xf
	v_add_f32_dpp v151, v151, v151 row_ror:2 row_mask:0xf bank_mask:0xf
	v_add_f32_dpp v152, v152, v152 row_ror:2 row_mask:0xf bank_mask:0xf
	v_add_f32_dpp v153, v153, v153 row_ror:2 row_mask:0xf bank_mask:0xf
	v_add_f32_dpp v154, v154, v154 row_ror:2 row_mask:0xf bank_mask:0xf
	v_add_f32_dpp v155, v155, v155 row_ror:2 row_mask:0xf bank_mask:0xf
	v_add_f32_dpp v148, v148, v148 row_ror:1 row_mask:0xf bank_mask:0xf
	v_add_f32_dpp v149, v149, v149 row_ror:1 row_mask:0xf bank_mask:0xf
	v_add_f32_dpp v150, v150, v150 row_ror:1 row_mask:0xf bank_mask:0xf
	v_add_f32_dpp v151, v151, v151 row_ror:1 row_mask:0xf bank_mask:0xf
	v_add_f32_dpp v152, v152, v152 row_ror:1 row_mask:0xf bank_mask:0xf
	v_add_f32_dpp v153, v153, v153 row_ror:1 row_mask:0xf bank_mask:0xf
	v_add_f32_dpp v154, v154, v154 row_ror:1 row_mask:0xf bank_mask:0xf
	v_add_f32_dpp v155, v155, v155 row_ror:1 row_mask:0xf bank_mask:0xf
	v_mov_b32_e32 v156, v148
	v_mov_b32_e32 v157, v149
	v_mov_b32_e32 v158, v150
	v_mov_b32_e32 v159, v151
	v_mov_b32_e32 v160, v152
	v_mov_b32_e32 v161, v153
	v_mov_b32_e32 v162, v154
	v_mov_b32_e32 v163, v155
	s_nop 1
	v_permlane16_swap_b32_e32 v156, v148
	v_permlane16_swap_b32_e32 v157, v149
	v_permlane16_swap_b32_e32 v158, v150
	v_permlane16_swap_b32_e32 v159, v151
	v_permlane16_swap_b32_e32 v160, v152
	v_permlane16_swap_b32_e32 v161, v153
	v_permlane16_swap_b32_e32 v162, v154
	v_permlane16_swap_b32_e32 v163, v155
	v_add_f32_e32 v148, v148, v156
	v_add_f32_e32 v149, v149, v157
	v_add_f32_e32 v150, v150, v158
	v_add_f32_e32 v151, v151, v159
	v_add_f32_e32 v152, v152, v160
	v_add_f32_e32 v153, v153, v161
	v_add_f32_e32 v154, v154, v162
	v_add_f32_e32 v155, v155, v163
	v_mov_b32_e32 v156, v148
	v_mov_b32_e32 v157, v149
	v_mov_b32_e32 v158, v150
	v_mov_b32_e32 v159, v151
	v_mov_b32_e32 v160, v152
	v_mov_b32_e32 v161, v153
	v_mov_b32_e32 v162, v154
	v_mov_b32_e32 v163, v155
	s_nop 1
	v_permlane32_swap_b32_e32 v156, v148
	v_permlane32_swap_b32_e32 v157, v149
	v_permlane32_swap_b32_e32 v158, v150
	v_permlane32_swap_b32_e32 v159, v151
	v_permlane32_swap_b32_e32 v160, v152
	v_permlane32_swap_b32_e32 v161, v153
	v_permlane32_swap_b32_e32 v162, v154
	v_permlane32_swap_b32_e32 v163, v155
	v_add_f32_e32 v148, v148, v156
	v_add_f32_e32 v149, v149, v157
	v_add_f32_e32 v150, v150, v158
	v_add_f32_e32 v151, v151, v159
	v_add_f32_e32 v152, v152, v160
	v_add_f32_e32 v153, v153, v161
	v_add_f32_e32 v154, v154, v162
	v_add_f32_e32 v155, v155, v163
	v_fma_f32 v148, v148, s8, v167
	v_fma_f32 v149, v149, s8, v167
	v_fma_f32 v150, v150, s8, v167
	v_fma_f32 v151, v151, s8, v167
	v_fma_f32 v152, v152, s8, v167
	v_fma_f32 v153, v153, s8, v167
	v_fma_f32 v154, v154, s8, v167
	v_fma_f32 v155, v155, s8, v167
	v_rsq_f32_e32 v148, v148
	v_rsq_f32_e32 v149, v149
	v_rsq_f32_e32 v150, v150
	v_rsq_f32_e32 v151, v151
	v_rsq_f32_e32 v152, v152
	v_rsq_f32_e32 v153, v153
	v_rsq_f32_e32 v154, v154
	v_rsq_f32_e32 v155, v155
	s_nop 0
	v_lshlrev_b32_e32 v82, 16, v84
	v_and_b32_e32 v83, 0xffff0000, v84
	v_mul_f32_e32 v82, v82, v148
	v_mul_f32_e32 v83, v83, v148
	v_cvt_pk_bf16_f32 v84, v82, v83
	v_lshlrev_b32_e32 v82, 16, v85
	v_and_b32_e32 v83, 0xffff0000, v85
	v_mul_f32_e32 v82, v82, v148
	v_mul_f32_e32 v83, v83, v148
	v_cvt_pk_bf16_f32 v85, v82, v83
	v_lshlrev_b32_e32 v82, 16, v86
	v_and_b32_e32 v83, 0xffff0000, v86
	v_mul_f32_e32 v82, v82, v148
	v_mul_f32_e32 v83, v83, v148
	v_cvt_pk_bf16_f32 v86, v82, v83
	v_lshlrev_b32_e32 v82, 16, v87
	v_and_b32_e32 v83, 0xffff0000, v87
	v_mul_f32_e32 v82, v82, v148
	v_mul_f32_e32 v83, v83, v148
	v_cvt_pk_bf16_f32 v87, v82, v83
	v_lshlrev_b32_e32 v82, 16, v88
	v_and_b32_e32 v83, 0xffff0000, v88
	v_mul_f32_e32 v82, v82, v148
	v_mul_f32_e32 v83, v83, v148
	v_cvt_pk_bf16_f32 v88, v82, v83
	v_lshlrev_b32_e32 v82, 16, v89
	v_and_b32_e32 v83, 0xffff0000, v89
	v_mul_f32_e32 v82, v82, v148
	v_mul_f32_e32 v83, v83, v148
	v_cvt_pk_bf16_f32 v89, v82, v83
	v_lshlrev_b32_e32 v82, 16, v90
	v_and_b32_e32 v83, 0xffff0000, v90
	v_mul_f32_e32 v82, v82, v148
	v_mul_f32_e32 v83, v83, v148
	v_cvt_pk_bf16_f32 v90, v82, v83
	v_lshlrev_b32_e32 v82, 16, v91
	v_and_b32_e32 v83, 0xffff0000, v91
	v_mul_f32_e32 v82, v82, v148
	v_mul_f32_e32 v83, v83, v148
	v_cvt_pk_bf16_f32 v91, v82, v83
	ds_write2st64_b64 v10, v[84:85], v[86:87] offset1:1
	ds_write2st64_b64 v10, v[88:89], v[90:91] offset0:2 offset1:3
	v_add_u32_e32 v10, 0x808, v10
	v_lshlrev_b32_e32 v82, 16, v92
	v_and_b32_e32 v83, 0xffff0000, v92
	v_mul_f32_e32 v82, v82, v149
	v_mul_f32_e32 v83, v83, v149
	v_cvt_pk_bf16_f32 v92, v82, v83
	v_lshlrev_b32_e32 v82, 16, v93
	v_and_b32_e32 v83, 0xffff0000, v93
	v_mul_f32_e32 v82, v82, v149
	v_mul_f32_e32 v83, v83, v149
	v_cvt_pk_bf16_f32 v93, v82, v83
	v_lshlrev_b32_e32 v82, 16, v94
	v_and_b32_e32 v83, 0xffff0000, v94
	v_mul_f32_e32 v82, v82, v149
	v_mul_f32_e32 v83, v83, v149
	v_cvt_pk_bf16_f32 v94, v82, v83
	v_lshlrev_b32_e32 v82, 16, v95
	v_and_b32_e32 v83, 0xffff0000, v95
	v_mul_f32_e32 v82, v82, v149
	v_mul_f32_e32 v83, v83, v149
	v_cvt_pk_bf16_f32 v95, v82, v83
	v_lshlrev_b32_e32 v82, 16, v96
	v_and_b32_e32 v83, 0xffff0000, v96
	v_mul_f32_e32 v82, v82, v149
	v_mul_f32_e32 v83, v83, v149
	v_cvt_pk_bf16_f32 v96, v82, v83
	v_lshlrev_b32_e32 v82, 16, v97
	v_and_b32_e32 v83, 0xffff0000, v97
	v_mul_f32_e32 v82, v82, v149
	v_mul_f32_e32 v83, v83, v149
	v_cvt_pk_bf16_f32 v97, v82, v83
	v_lshlrev_b32_e32 v82, 16, v98
	v_and_b32_e32 v83, 0xffff0000, v98
	v_mul_f32_e32 v82, v82, v149
	v_mul_f32_e32 v83, v83, v149
	v_cvt_pk_bf16_f32 v98, v82, v83
	v_lshlrev_b32_e32 v82, 16, v99
	v_and_b32_e32 v83, 0xffff0000, v99
	v_mul_f32_e32 v82, v82, v149
	v_mul_f32_e32 v83, v83, v149
	v_cvt_pk_bf16_f32 v99, v82, v83
	ds_write2st64_b64 v10, v[92:93], v[94:95] offset1:1
	ds_write2st64_b64 v10, v[96:97], v[98:99] offset0:2 offset1:3
	v_add_u32_e32 v10, 0x808, v10
	v_lshlrev_b32_e32 v82, 16, v100
	v_and_b32_e32 v83, 0xffff0000, v100
	v_mul_f32_e32 v82, v82, v150
	v_mul_f32_e32 v83, v83, v150
	v_cvt_pk_bf16_f32 v100, v82, v83
	v_lshlrev_b32_e32 v82, 16, v101
	v_and_b32_e32 v83, 0xffff0000, v101
	v_mul_f32_e32 v82, v82, v150
	v_mul_f32_e32 v83, v83, v150
	v_cvt_pk_bf16_f32 v101, v82, v83
	v_lshlrev_b32_e32 v82, 16, v102
	v_and_b32_e32 v83, 0xffff0000, v102
	v_mul_f32_e32 v82, v82, v150
	v_mul_f32_e32 v83, v83, v150
	v_cvt_pk_bf16_f32 v102, v82, v83
	v_lshlrev_b32_e32 v82, 16, v103
	v_and_b32_e32 v83, 0xffff0000, v103
	v_mul_f32_e32 v82, v82, v150
	v_mul_f32_e32 v83, v83, v150
	v_cvt_pk_bf16_f32 v103, v82, v83
	v_lshlrev_b32_e32 v82, 16, v104
	v_and_b32_e32 v83, 0xffff0000, v104
	v_mul_f32_e32 v82, v82, v150
	v_mul_f32_e32 v83, v83, v150
	v_cvt_pk_bf16_f32 v104, v82, v83
	v_lshlrev_b32_e32 v82, 16, v105
	v_and_b32_e32 v83, 0xffff0000, v105
	v_mul_f32_e32 v82, v82, v150
	v_mul_f32_e32 v83, v83, v150
	v_cvt_pk_bf16_f32 v105, v82, v83
	v_lshlrev_b32_e32 v82, 16, v106
	v_and_b32_e32 v83, 0xffff0000, v106
	v_mul_f32_e32 v82, v82, v150
	v_mul_f32_e32 v83, v83, v150
	v_cvt_pk_bf16_f32 v106, v82, v83
	v_lshlrev_b32_e32 v82, 16, v107
	v_and_b32_e32 v83, 0xffff0000, v107
	v_mul_f32_e32 v82, v82, v150
	v_mul_f32_e32 v83, v83, v150
	v_cvt_pk_bf16_f32 v107, v82, v83
	ds_write2st64_b64 v10, v[100:101], v[102:103] offset1:1
	ds_write2st64_b64 v10, v[104:105], v[106:107] offset0:2 offset1:3
	v_add_u32_e32 v10, 0x808, v10
	v_lshlrev_b32_e32 v82, 16, v108
	v_and_b32_e32 v83, 0xffff0000, v108
	v_mul_f32_e32 v82, v82, v151
	v_mul_f32_e32 v83, v83, v151
	v_cvt_pk_bf16_f32 v108, v82, v83
	v_lshlrev_b32_e32 v82, 16, v109
	v_and_b32_e32 v83, 0xffff0000, v109
	v_mul_f32_e32 v82, v82, v151
	v_mul_f32_e32 v83, v83, v151
	v_cvt_pk_bf16_f32 v109, v82, v83
	v_lshlrev_b32_e32 v82, 16, v110
	v_and_b32_e32 v83, 0xffff0000, v110
	v_mul_f32_e32 v82, v82, v151
	v_mul_f32_e32 v83, v83, v151
	v_cvt_pk_bf16_f32 v110, v82, v83
	v_lshlrev_b32_e32 v82, 16, v111
	v_and_b32_e32 v83, 0xffff0000, v111
	v_mul_f32_e32 v82, v82, v151
	v_mul_f32_e32 v83, v83, v151
	v_cvt_pk_bf16_f32 v111, v82, v83
	v_lshlrev_b32_e32 v82, 16, v112
	v_and_b32_e32 v83, 0xffff0000, v112
	v_mul_f32_e32 v82, v82, v151
	v_mul_f32_e32 v83, v83, v151
	v_cvt_pk_bf16_f32 v112, v82, v83
	v_lshlrev_b32_e32 v82, 16, v113
	v_and_b32_e32 v83, 0xffff0000, v113
	v_mul_f32_e32 v82, v82, v151
	v_mul_f32_e32 v83, v83, v151
	v_cvt_pk_bf16_f32 v113, v82, v83
	v_lshlrev_b32_e32 v82, 16, v114
	v_and_b32_e32 v83, 0xffff0000, v114
	v_mul_f32_e32 v82, v82, v151
	v_mul_f32_e32 v83, v83, v151
	v_cvt_pk_bf16_f32 v114, v82, v83
	v_lshlrev_b32_e32 v82, 16, v115
	v_and_b32_e32 v83, 0xffff0000, v115
	v_mul_f32_e32 v82, v82, v151
	v_mul_f32_e32 v83, v83, v151
	v_cvt_pk_bf16_f32 v115, v82, v83
	ds_write2st64_b64 v10, v[108:109], v[110:111] offset1:1
	ds_write2st64_b64 v10, v[112:113], v[114:115] offset0:2 offset1:3
	v_add_u32_e32 v10, 0x808, v10
	v_lshlrev_b32_e32 v82, 16, v116
	v_and_b32_e32 v83, 0xffff0000, v116
	v_mul_f32_e32 v82, v82, v152
	v_mul_f32_e32 v83, v83, v152
	v_cvt_pk_bf16_f32 v116, v82, v83
	v_lshlrev_b32_e32 v82, 16, v117
	v_and_b32_e32 v83, 0xffff0000, v117
	v_mul_f32_e32 v82, v82, v152
	v_mul_f32_e32 v83, v83, v152
	v_cvt_pk_bf16_f32 v117, v82, v83
	v_lshlrev_b32_e32 v82, 16, v118
	v_and_b32_e32 v83, 0xffff0000, v118
	v_mul_f32_e32 v82, v82, v152
	v_mul_f32_e32 v83, v83, v152
	v_cvt_pk_bf16_f32 v118, v82, v83
	v_lshlrev_b32_e32 v82, 16, v119
	v_and_b32_e32 v83, 0xffff0000, v119
	v_mul_f32_e32 v82, v82, v152
	v_mul_f32_e32 v83, v83, v152
	v_cvt_pk_bf16_f32 v119, v82, v83
	v_lshlrev_b32_e32 v82, 16, v120
	v_and_b32_e32 v83, 0xffff0000, v120
	v_mul_f32_e32 v82, v82, v152
	v_mul_f32_e32 v83, v83, v152
	v_cvt_pk_bf16_f32 v120, v82, v83
	v_lshlrev_b32_e32 v82, 16, v121
	v_and_b32_e32 v83, 0xffff0000, v121
	v_mul_f32_e32 v82, v82, v152
	v_mul_f32_e32 v83, v83, v152
	v_cvt_pk_bf16_f32 v121, v82, v83
	v_lshlrev_b32_e32 v82, 16, v122
	v_and_b32_e32 v83, 0xffff0000, v122
	v_mul_f32_e32 v82, v82, v152
	v_mul_f32_e32 v83, v83, v152
	v_cvt_pk_bf16_f32 v122, v82, v83
	v_lshlrev_b32_e32 v82, 16, v123
	v_and_b32_e32 v83, 0xffff0000, v123
	v_mul_f32_e32 v82, v82, v152
	v_mul_f32_e32 v83, v83, v152
	v_cvt_pk_bf16_f32 v123, v82, v83
	ds_write2st64_b64 v10, v[116:117], v[118:119] offset1:1
	ds_write2st64_b64 v10, v[120:121], v[122:123] offset0:2 offset1:3
	v_add_u32_e32 v10, 0x808, v10
	v_lshlrev_b32_e32 v82, 16, v124
	v_and_b32_e32 v83, 0xffff0000, v124
	v_mul_f32_e32 v82, v82, v153
	v_mul_f32_e32 v83, v83, v153
	v_cvt_pk_bf16_f32 v124, v82, v83
	v_lshlrev_b32_e32 v82, 16, v125
	v_and_b32_e32 v83, 0xffff0000, v125
	v_mul_f32_e32 v82, v82, v153
	v_mul_f32_e32 v83, v83, v153
	v_cvt_pk_bf16_f32 v125, v82, v83
	v_lshlrev_b32_e32 v82, 16, v126
	v_and_b32_e32 v83, 0xffff0000, v126
	v_mul_f32_e32 v82, v82, v153
	v_mul_f32_e32 v83, v83, v153
	v_cvt_pk_bf16_f32 v126, v82, v83
	v_lshlrev_b32_e32 v82, 16, v127
	v_and_b32_e32 v83, 0xffff0000, v127
	v_mul_f32_e32 v82, v82, v153
	v_mul_f32_e32 v83, v83, v153
	v_cvt_pk_bf16_f32 v127, v82, v83
	v_lshlrev_b32_e32 v82, 16, v128
	v_and_b32_e32 v83, 0xffff0000, v128
	v_mul_f32_e32 v82, v82, v153
	v_mul_f32_e32 v83, v83, v153
	v_cvt_pk_bf16_f32 v128, v82, v83
	v_lshlrev_b32_e32 v82, 16, v129
	v_and_b32_e32 v83, 0xffff0000, v129
	v_mul_f32_e32 v82, v82, v153
	v_mul_f32_e32 v83, v83, v153
	v_cvt_pk_bf16_f32 v129, v82, v83
	v_lshlrev_b32_e32 v82, 16, v130
	v_and_b32_e32 v83, 0xffff0000, v130
	v_mul_f32_e32 v82, v82, v153
	v_mul_f32_e32 v83, v83, v153
	v_cvt_pk_bf16_f32 v130, v82, v83
	v_lshlrev_b32_e32 v82, 16, v131
	v_and_b32_e32 v83, 0xffff0000, v131
	v_mul_f32_e32 v82, v82, v153
	v_mul_f32_e32 v83, v83, v153
	v_cvt_pk_bf16_f32 v131, v82, v83
	ds_write2st64_b64 v10, v[124:125], v[126:127] offset1:1
	ds_write2st64_b64 v10, v[128:129], v[130:131] offset0:2 offset1:3
	v_add_u32_e32 v10, 0x808, v10
	v_lshlrev_b32_e32 v82, 16, v132
	v_and_b32_e32 v83, 0xffff0000, v132
	v_mul_f32_e32 v82, v82, v154
	v_mul_f32_e32 v83, v83, v154
	v_cvt_pk_bf16_f32 v132, v82, v83
	v_lshlrev_b32_e32 v82, 16, v133
	v_and_b32_e32 v83, 0xffff0000, v133
	v_mul_f32_e32 v82, v82, v154
	v_mul_f32_e32 v83, v83, v154
	v_cvt_pk_bf16_f32 v133, v82, v83
	v_lshlrev_b32_e32 v82, 16, v134
	v_and_b32_e32 v83, 0xffff0000, v134
	v_mul_f32_e32 v82, v82, v154
	v_mul_f32_e32 v83, v83, v154
	v_cvt_pk_bf16_f32 v134, v82, v83
	v_lshlrev_b32_e32 v82, 16, v135
	v_and_b32_e32 v83, 0xffff0000, v135
	v_mul_f32_e32 v82, v82, v154
	v_mul_f32_e32 v83, v83, v154
	v_cvt_pk_bf16_f32 v135, v82, v83
	v_lshlrev_b32_e32 v82, 16, v136
	v_and_b32_e32 v83, 0xffff0000, v136
	v_mul_f32_e32 v82, v82, v154
	v_mul_f32_e32 v83, v83, v154
	v_cvt_pk_bf16_f32 v136, v82, v83
	v_lshlrev_b32_e32 v82, 16, v137
	v_and_b32_e32 v83, 0xffff0000, v137
	v_mul_f32_e32 v82, v82, v154
	v_mul_f32_e32 v83, v83, v154
	v_cvt_pk_bf16_f32 v137, v82, v83
	v_lshlrev_b32_e32 v82, 16, v138
	v_and_b32_e32 v83, 0xffff0000, v138
	v_mul_f32_e32 v82, v82, v154
	v_mul_f32_e32 v83, v83, v154
	v_cvt_pk_bf16_f32 v138, v82, v83
	v_lshlrev_b32_e32 v82, 16, v139
	v_and_b32_e32 v83, 0xffff0000, v139
	v_mul_f32_e32 v82, v82, v154
	v_mul_f32_e32 v83, v83, v154
	v_cvt_pk_bf16_f32 v139, v82, v83
	ds_write2st64_b64 v10, v[132:133], v[134:135] offset1:1
	ds_write2st64_b64 v10, v[136:137], v[138:139] offset0:2 offset1:3
	v_add_u32_e32 v10, 0x808, v10
	v_lshlrev_b32_e32 v82, 16, v140
	v_and_b32_e32 v83, 0xffff0000, v140
	v_mul_f32_e32 v82, v82, v155
	v_mul_f32_e32 v83, v83, v155
	v_cvt_pk_bf16_f32 v140, v82, v83
	v_lshlrev_b32_e32 v82, 16, v141
	v_and_b32_e32 v83, 0xffff0000, v141
	v_mul_f32_e32 v82, v82, v155
	v_mul_f32_e32 v83, v83, v155
	v_cvt_pk_bf16_f32 v141, v82, v83
	v_lshlrev_b32_e32 v82, 16, v142
	v_and_b32_e32 v83, 0xffff0000, v142
	v_mul_f32_e32 v82, v82, v155
	v_mul_f32_e32 v83, v83, v155
	v_cvt_pk_bf16_f32 v142, v82, v83
	v_lshlrev_b32_e32 v82, 16, v143
	v_and_b32_e32 v83, 0xffff0000, v143
	v_mul_f32_e32 v82, v82, v155
	v_mul_f32_e32 v83, v83, v155
	v_cvt_pk_bf16_f32 v143, v82, v83
	v_lshlrev_b32_e32 v82, 16, v144
	v_and_b32_e32 v83, 0xffff0000, v144
	v_mul_f32_e32 v82, v82, v155
	v_mul_f32_e32 v83, v83, v155
	v_cvt_pk_bf16_f32 v144, v82, v83
	v_lshlrev_b32_e32 v82, 16, v145
	v_and_b32_e32 v83, 0xffff0000, v145
	v_mul_f32_e32 v82, v82, v155
	v_mul_f32_e32 v83, v83, v155
	v_cvt_pk_bf16_f32 v145, v82, v83
	v_lshlrev_b32_e32 v82, 16, v146
	v_and_b32_e32 v83, 0xffff0000, v146
	v_mul_f32_e32 v82, v82, v155
	v_mul_f32_e32 v83, v83, v155
	v_cvt_pk_bf16_f32 v146, v82, v83
	v_lshlrev_b32_e32 v82, 16, v147
	v_and_b32_e32 v83, 0xffff0000, v147
	v_mul_f32_e32 v82, v82, v155
	v_mul_f32_e32 v83, v83, v155
	v_cvt_pk_bf16_f32 v147, v82, v83
	ds_write2st64_b64 v10, v[140:141], v[142:143] offset1:1
	ds_write2st64_b64 v10, v[144:145], v[146:147] offset0:2 offset1:3
	v_add_u32_e32 v10, 0x808, v10
	s_waitcnt lgkmcnt(0)
	s_barrier
	v_mbcnt_lo_u32_b32 v91, -1, 0
	v_mbcnt_hi_u32_b32 v91, -1, v91
	v_readlane_b32 s9, v254, 63
	v_and_b32_e32 v88, 7, v91
	v_lshrrev_b32_e32 v89, 3, v91
	v_lshl_add_u32 v89, s9, 3, v89
	v_mul_u32_u24_e32 v90, 16448, v88
	v_lshl_add_u32 v90, v89, 2, v90
	v_mul_u32_u24_e32 v89, 0xc000, v89
	v_lshl_add_u32 v89, v88, 4, v89
	v_add_u32_e32 v88, 0x6000, v89
	s_lshl_b32 s8, s0, 7
	v_readlane_b32 s10, v255, 7
	v_readlane_b32 s11, v255, 8
	s_add_u32 s10, s10, 0x10000000
	s_addc_u32 s11, s11, 0
	s_add_u32 s10, s10, s8
	s_addc_u32 s11, s11, 0
	s_mov_b32 s1, 0x5040100
	s_mov_b32 s3, 0x7060302
	ds_read_b32 v70, v90 offset:0
	ds_read_b32 v71, v90 offset:2056
	ds_read_b32 v72, v90 offset:4112
	ds_read_b32 v73, v90 offset:6168
	ds_read_b32 v74, v90 offset:8224
	ds_read_b32 v75, v90 offset:10280
	ds_read_b32 v76, v90 offset:12336
	ds_read_b32 v77, v90 offset:14392
	ds_read_b32 v92, v90 offset:256
	ds_read_b32 v93, v90 offset:2312
	ds_read_b32 v94, v90 offset:4368
	ds_read_b32 v95, v90 offset:6424
	ds_read_b32 v96, v90 offset:8480
	ds_read_b32 v97, v90 offset:10536
	ds_read_b32 v98, v90 offset:12592
	ds_read_b32 v99, v90 offset:14648
	s_waitcnt lgkmcnt(8)
	v_perm_b32 v80, v71, v70, s1
	v_perm_b32 v81, v73, v72, s1
	v_perm_b32 v82, v75, v74, s1
	v_perm_b32 v83, v77, v76, s1
	v_perm_b32 v84, v71, v70, s3
	v_perm_b32 v85, v73, v72, s3
	v_perm_b32 v86, v75, v74, s3
	v_perm_b32 v87, v77, v76, s3
	global_store_dwordx4 v89, v[80:83], s[10:11]
	global_store_dwordx4 v88, v[84:87], s[10:11]
	s_add_u32 s10, s10, 0x300000
	s_addc_u32 s11, s11, 0
	ds_read_b32 v70, v90 offset:512
	ds_read_b32 v71, v90 offset:2568
	ds_read_b32 v72, v90 offset:4624
	ds_read_b32 v73, v90 offset:6680
	ds_read_b32 v74, v90 offset:8736
	ds_read_b32 v75, v90 offset:10792
	ds_read_b32 v76, v90 offset:12848
	ds_read_b32 v77, v90 offset:14904
	s_waitcnt lgkmcnt(8)
	v_perm_b32 v80, v93, v92, s1
	v_perm_b32 v81, v95, v94, s1
	v_perm_b32 v82, v97, v96, s1
	v_perm_b32 v83, v99, v98, s1
	v_perm_b32 v84, v93, v92, s3
	v_perm_b32 v85, v95, v94, s3
	v_perm_b32 v86, v97, v96, s3
	v_perm_b32 v87, v99, v98, s3
	global_store_dwordx4 v89, v[80:83], s[10:11]
	global_store_dwordx4 v88, v[84:87], s[10:11]
	s_add_u32 s10, s10, 0x300000
	s_addc_u32 s11, s11, 0
	ds_read_b32 v92, v90 offset:768
	ds_read_b32 v93, v90 offset:2824
	ds_read_b32 v94, v90 offset:4880
	ds_read_b32 v95, v90 offset:6936
	ds_read_b32 v96, v90 offset:8992
	ds_read_b32 v97, v90 offset:11048
	ds_read_b32 v98, v90 offset:13104
	ds_read_b32 v99, v90 offset:15160
	s_waitcnt lgkmcnt(8)
	v_perm_b32 v80, v71, v70, s1
	v_perm_b32 v81, v73, v72, s1
	v_perm_b32 v82, v75, v74, s1
	v_perm_b32 v83, v77, v76, s1
	v_perm_b32 v84, v71, v70, s3
	v_perm_b32 v85, v73, v72, s3
	v_perm_b32 v86, v75, v74, s3
	v_perm_b32 v87, v77, v76, s3
	global_store_dwordx4 v89, v[80:83], s[10:11]
	global_store_dwordx4 v88, v[84:87], s[10:11]
	s_add_u32 s10, s10, 0x300000
	s_addc_u32 s11, s11, 0
	ds_read_b32 v70, v90 offset:1024
	ds_read_b32 v71, v90 offset:3080
	ds_read_b32 v72, v90 offset:5136
	ds_read_b32 v73, v90 offset:7192
	ds_read_b32 v74, v90 offset:9248
	ds_read_b32 v75, v90 offset:11304
	ds_read_b32 v76, v90 offset:13360
	ds_read_b32 v77, v90 offset:15416
	s_waitcnt lgkmcnt(8)
	v_perm_b32 v80, v93, v92, s1
	v_perm_b32 v81, v95, v94, s1
	v_perm_b32 v82, v97, v96, s1
	v_perm_b32 v83, v99, v98, s1
	v_perm_b32 v84, v93, v92, s3
	v_perm_b32 v85, v95, v94, s3
	v_perm_b32 v86, v97, v96, s3
	v_perm_b32 v87, v99, v98, s3
	global_store_dwordx4 v89, v[80:83], s[10:11]
	global_store_dwordx4 v88, v[84:87], s[10:11]
	s_add_u32 s10, s10, 0x300000
	s_addc_u32 s11, s11, 0
	ds_read_b32 v92, v90 offset:1280
	ds_read_b32 v93, v90 offset:3336
	ds_read_b32 v94, v90 offset:5392
	ds_read_b32 v95, v90 offset:7448
	ds_read_b32 v96, v90 offset:9504
	ds_read_b32 v97, v90 offset:11560
	ds_read_b32 v98, v90 offset:13616
	ds_read_b32 v99, v90 offset:15672
	s_waitcnt lgkmcnt(8)
	v_perm_b32 v80, v71, v70, s1
	v_perm_b32 v81, v73, v72, s1
	v_perm_b32 v82, v75, v74, s1
	v_perm_b32 v83, v77, v76, s1
	v_perm_b32 v84, v71, v70, s3
	v_perm_b32 v85, v73, v72, s3
	v_perm_b32 v86, v75, v74, s3
	v_perm_b32 v87, v77, v76, s3
	global_store_dwordx4 v89, v[80:83], s[10:11]
	global_store_dwordx4 v88, v[84:87], s[10:11]
	s_add_u32 s10, s10, 0x300000
	s_addc_u32 s11, s11, 0
	ds_read_b32 v70, v90 offset:1536
	ds_read_b32 v71, v90 offset:3592
	ds_read_b32 v72, v90 offset:5648
	ds_read_b32 v73, v90 offset:7704
	ds_read_b32 v74, v90 offset:9760
	ds_read_b32 v75, v90 offset:11816
	ds_read_b32 v76, v90 offset:13872
	ds_read_b32 v77, v90 offset:15928
	s_waitcnt lgkmcnt(8)
	v_perm_b32 v80, v93, v92, s1
	v_perm_b32 v81, v95, v94, s1
	v_perm_b32 v82, v97, v96, s1
	v_perm_b32 v83, v99, v98, s1
	v_perm_b32 v84, v93, v92, s3
	v_perm_b32 v85, v95, v94, s3
	v_perm_b32 v86, v97, v96, s3
	v_perm_b32 v87, v99, v98, s3
	global_store_dwordx4 v89, v[80:83], s[10:11]
	global_store_dwordx4 v88, v[84:87], s[10:11]
	s_add_u32 s10, s10, 0x300000
	s_addc_u32 s11, s11, 0
	ds_read_b32 v92, v90 offset:1792
	ds_read_b32 v93, v90 offset:3848
	ds_read_b32 v94, v90 offset:5904
	ds_read_b32 v95, v90 offset:7960
	ds_read_b32 v96, v90 offset:10016
	ds_read_b32 v97, v90 offset:12072
	ds_read_b32 v98, v90 offset:14128
	ds_read_b32 v99, v90 offset:16184
	s_waitcnt lgkmcnt(8)
	v_perm_b32 v80, v71, v70, s1
	v_perm_b32 v81, v73, v72, s1
	v_perm_b32 v82, v75, v74, s1
	v_perm_b32 v83, v77, v76, s1
	v_perm_b32 v84, v71, v70, s3
	v_perm_b32 v85, v73, v72, s3
	v_perm_b32 v86, v75, v74, s3
	v_perm_b32 v87, v77, v76, s3
	global_store_dwordx4 v89, v[80:83], s[10:11]
	global_store_dwordx4 v88, v[84:87], s[10:11]
	s_add_u32 s10, s10, 0x300000
	s_addc_u32 s11, s11, 0
	s_waitcnt lgkmcnt(0)
	v_perm_b32 v80, v93, v92, s1
	v_perm_b32 v81, v95, v94, s1
	v_perm_b32 v82, v97, v96, s1
	v_perm_b32 v83, v99, v98, s1
	v_perm_b32 v84, v93, v92, s3
	v_perm_b32 v85, v95, v94, s3
	v_perm_b32 v86, v97, v96, s3
	v_perm_b32 v87, v99, v98, s3
	global_store_dwordx4 v89, v[80:83], s[10:11]
	global_store_dwordx4 v88, v[84:87], s[10:11]
	s_add_i32 s0, s0, s78
	s_add_i32 s6, s6, s35
	s_cmpk_gt_i32 s0, 0xbf
	s_barrier
	s_cbranch_scc0 .LBB0_119

.LBB0_896:
	s_lshl_b32 s8, s7, 6
	v_readlane_b32 s9, v254, 63
	s_lshl_b32 s3, s9, 3
	s_add_i32 s16, s8, s3
	s_mov_b32 s17, 0
	s_sub_i32 s1, s8, 0x1800
	s_max_i32 s1, s1, 0
	s_lshr_b32 s1, s1, 11
	s_ashr_i32 s0, s80, 2
	s_and_b32 s6, s80, 3
	s_mul_i32 s3, s0, 3
	s_add_i32 s8, s3, s6
	v_readlane_b32 s10, v255, 14
	v_readlane_b32 s11, v255, 15
	s_load_dwordx2 s[12:13], s[10:11], 0x58
	s_add_i32 s3, s3, s1
	s_mul_i32 s3, s3, 0x9000
	s_mul_i32 s14, s6, 0x3000
	s_add_i32 s3, s3, s14
	s_add_i32 s3, s3, 0x100000
	v_readlane_b32 s18, v255, 7
	v_readlane_b32 s19, v255, 8
	s_add_u32 s18, s18, s3
	s_addc_u32 s19, s19, 0
	v_lshrrev_b32_e32 v200, 2, v18
	v_lshlrev_b32_e32 v201, 5, v200
	v_lshlrev_b32_e32 v202, 4, v200
	s_mul_i32 s9, s9, 16448
	v_add_u32_e32 v202, s9, v202
	s_lshl_b32 s8, s8, 12
	s_add_u32 s14, s18, 0x1000
	s_addc_u32 s15, s19, 0
	s_waitcnt lgkmcnt(0)
	s_add_u32 s12, s12, s8
	s_addc_u32 s13, s13, 0
	global_load_dwordx4 v[134:137], v201, s[12:13] offset:0
	global_load_dwordx4 v[150:153], v201, s[14:15] offset:0
	global_load_dwordx4 v[170:173], v201, s[18:19] offset:0
	global_load_dwordx4 v[138:141], v201, s[12:13] offset:16
	global_load_dwordx4 v[154:157], v201, s[14:15] offset:16
	global_load_dwordx4 v[174:177], v201, s[18:19] offset:16
	global_load_dwordx4 v[142:145], v201, s[12:13] offset:2048
	global_load_dwordx4 v[158:161], v201, s[14:15] offset:2048
	global_load_dwordx4 v[178:181], v201, s[18:19] offset:2048
	global_load_dwordx4 v[146:149], v201, s[12:13] offset:2064
	global_load_dwordx4 v[162:165], v201, s[14:15] offset:2064
	global_load_dwordx4 v[182:185], v201, s[18:19] offset:2064
	v_readlane_b32 s0, v254, 63
	s_cmp_lg_u32 s0, 0
	s_cbranch_scc1 .Lnt_bar
	s_lshr_b32 s0, s7, 2
	v_readlane_b32 s1, v254, 61
	s_add_i32 s1, s1, -1
	s_lshl_b32 s1, s1, 8
	s_lshl_b32 s0, s0, 2
	s_add_i32 s0, s0, s1
	s_add_i32 s0, s0, 0x10000
	v_readlane_b32 s10, v255, 7
	v_readlane_b32 s11, v255, 8
	s_add_u32 s10, s10, s0
	s_addc_u32 s11, s11, 0
	s_mov_b32 s0, 0

.Lnt_bar:
	s_barrier
	v_readlane_b32 s10, v255, 5
	v_readlane_b32 s11, v255, 6
	s_lshl_b64 s[12:13], s[16:17], 12
	s_add_u32 s10, s10, s12
	s_addc_u32 s11, s11, s13
	s_mov_b32 s3, 0x3a800000
	global_load_dwordx4 v[70:73], v201, s[10:11] offset:0
	global_load_dwordx4 v[74:77], v201, s[10:11] offset:16
	global_load_dwordx4 v[78:81], v201, s[10:11] offset:2048
	global_load_dwordx4 v[82:85], v201, s[10:11] offset:2064
	s_add_u32 s10, s10, 0x1000
	s_addc_u32 s11, s11, 0
	global_load_dwordx4 v[86:89], v201, s[10:11] offset:0
	global_load_dwordx4 v[90:93], v201, s[10:11] offset:16
	global_load_dwordx4 v[94:97], v201, s[10:11] offset:2048
	global_load_dwordx4 v[98:101], v201, s[10:11] offset:2064
	s_add_u32 s10, s10, 0x1000
	s_addc_u32 s11, s11, 0
	global_load_dwordx4 v[102:105], v201, s[10:11] offset:0
	global_load_dwordx4 v[106:109], v201, s[10:11] offset:16
	global_load_dwordx4 v[110:113], v201, s[10:11] offset:2048
	global_load_dwordx4 v[114:117], v201, s[10:11] offset:2064
	s_add_u32 s10, s10, 0x1000
	s_addc_u32 s11, s11, 0
	global_load_dwordx4 v[118:121], v201, s[10:11] offset:0
	global_load_dwordx4 v[122:125], v201, s[10:11] offset:16
	global_load_dwordx4 v[126:129], v201, s[10:11] offset:2048
	global_load_dwordx4 v[130:133], v201, s[10:11] offset:2064
	s_add_u32 s10, s10, 0x1000
	s_addc_u32 s11, s11, 0
	s_waitcnt vmcnt(16)
	v_add_f32_e32 v150, 1.0, v150
	v_add_f32_e32 v151, 1.0, v151
	v_add_f32_e32 v152, 1.0, v152
	v_add_f32_e32 v153, 1.0, v153
	v_add_f32_e32 v154, 1.0, v154
	v_add_f32_e32 v155, 1.0, v155
	v_add_f32_e32 v156, 1.0, v156
	v_add_f32_e32 v157, 1.0, v157
	v_add_f32_e32 v158, 1.0, v158
	v_add_f32_e32 v159, 1.0, v159
	v_add_f32_e32 v160, 1.0, v160
	v_add_f32_e32 v161, 1.0, v161
	v_add_f32_e32 v162, 1.0, v162
	v_add_f32_e32 v163, 1.0, v163
	v_add_f32_e32 v164, 1.0, v164
	v_add_f32_e32 v165, 1.0, v165
	v_mul_f32_e32 v150, v134, v150
	v_mul_f32_e32 v151, v135, v151
	v_mul_f32_e32 v152, v136, v152
	v_mul_f32_e32 v153, v137, v153
	v_mul_f32_e32 v154, v138, v154
	v_mul_f32_e32 v155, v139, v155
	v_mul_f32_e32 v156, v140, v156
	v_mul_f32_e32 v157, v141, v157
	v_mul_f32_e32 v158, v142, v158
	v_mul_f32_e32 v159, v143, v159
	v_mul_f32_e32 v160, v144, v160
	v_mul_f32_e32 v161, v145, v161
	v_mul_f32_e32 v162, v146, v162
	v_mul_f32_e32 v163, v147, v163
	v_mul_f32_e32 v164, v148, v164
	v_mul_f32_e32 v165, v149, v165
	s_waitcnt vmcnt(12)
	v_mul_f32_e32 v186, v70, v70
	v_fmac_f32_e32 v186, v71, v71
	v_fmac_f32_e32 v186, v72, v72
	v_fmac_f32_e32 v186, v73, v73
	v_fmac_f32_e32 v186, v74, v74
	v_fmac_f32_e32 v186, v75, v75
	v_fmac_f32_e32 v186, v76, v76
	v_fmac_f32_e32 v186, v77, v77
	v_fmac_f32_e32 v186, v78, v78
	v_fmac_f32_e32 v186, v79, v79
	v_fmac_f32_e32 v186, v80, v80
	v_fmac_f32_e32 v186, v81, v81
	v_fmac_f32_e32 v186, v82, v82
	v_fmac_f32_e32 v186, v83, v83
	v_fmac_f32_e32 v186, v84, v84
	v_fmac_f32_e32 v186, v85, v85
	s_waitcnt vmcnt(8)
	v_mul_f32_e32 v187, v86, v86
	v_fmac_f32_e32 v187, v87, v87
	v_fmac_f32_e32 v187, v88, v88
	v_fmac_f32_e32 v187, v89, v89
	v_fmac_f32_e32 v187, v90, v90
	v_fmac_f32_e32 v187, v91, v91
	v_fmac_f32_e32 v187, v92, v92
	v_fmac_f32_e32 v187, v93, v93
	v_fmac_f32_e32 v187, v94, v94
	v_fmac_f32_e32 v187, v95, v95
	v_fmac_f32_e32 v187, v96, v96
	v_fmac_f32_e32 v187, v97, v97
	v_fmac_f32_e32 v187, v98, v98
	v_fmac_f32_e32 v187, v99, v99
	v_fmac_f32_e32 v187, v100, v100
	v_fmac_f32_e32 v187, v101, v101
	s_waitcnt vmcnt(4)
	v_mul_f32_e32 v188, v102, v102
	v_fmac_f32_e32 v188, v103, v103
	v_fmac_f32_e32 v188, v104, v104
	v_fmac_f32_e32 v188, v105, v105
	v_fmac_f32_e32 v188, v106, v106
	v_fmac_f32_e32 v188, v107, v107
	v_fmac_f32_e32 v188, v108, v108
	v_fmac_f32_e32 v188, v109, v109
	v_fmac_f32_e32 v188, v110, v110
	v_fmac_f32_e32 v188, v111, v111
	v_fmac_f32_e32 v188, v112, v112
	v_fmac_f32_e32 v188, v113, v113
	v_fmac_f32_e32 v188, v114, v114
	v_fmac_f32_e32 v188, v115, v115
	v_fmac_f32_e32 v188, v116, v116
	v_fmac_f32_e32 v188, v117, v117
	s_waitcnt vmcnt(0)
	v_mul_f32_e32 v189, v118, v118
	v_fmac_f32_e32 v189, v119, v119
	v_fmac_f32_e32 v189, v120, v120
	v_fmac_f32_e32 v189, v121, v121
	v_fmac_f32_e32 v189, v122, v122
	v_fmac_f32_e32 v189, v123, v123
	v_fmac_f32_e32 v189, v124, v124
	v_fmac_f32_e32 v189, v125, v125
	v_fmac_f32_e32 v189, v126, v126
	v_fmac_f32_e32 v189, v127, v127
	v_fmac_f32_e32 v189, v128, v128
	v_fmac_f32_e32 v189, v129, v129
	v_fmac_f32_e32 v189, v130, v130
	v_fmac_f32_e32 v189, v131, v131
	v_fmac_f32_e32 v189, v132, v132
	v_fmac_f32_e32 v189, v133, v133
	s_nop 1
	v_add_f32_dpp v186, v186, v186 row_ror:8 row_mask:0xf bank_mask:0xf
	v_add_f32_dpp v187, v187, v187 row_ror:8 row_mask:0xf bank_mask:0xf
	v_add_f32_dpp v188, v188, v188 row_ror:8 row_mask:0xf bank_mask:0xf
	v_add_f32_dpp v189, v189, v189 row_ror:8 row_mask:0xf bank_mask:0xf
	v_add_f32_dpp v186, v186, v186 row_ror:4 row_mask:0xf bank_mask:0xf
	v_add_f32_dpp v187, v187, v187 row_ror:4 row_mask:0xf bank_mask:0xf
	v_add_f32_dpp v188, v188, v188 row_ror:4 row_mask:0xf bank_mask:0xf
	v_add_f32_dpp v189, v189, v189 row_ror:4 row_mask:0xf bank_mask:0xf
	v_add_f32_dpp v186, v186, v186 row_ror:2 row_mask:0xf bank_mask:0xf
	v_add_f32_dpp v187, v187, v187 row_ror:2 row_mask:0xf bank_mask:0xf
	v_add_f32_dpp v188, v188, v188 row_ror:2 row_mask:0xf bank_mask:0xf
	v_add_f32_dpp v189, v189, v189 row_ror:2 row_mask:0xf bank_mask:0xf
	v_add_f32_dpp v186, v186, v186 row_ror:1 row_mask:0xf bank_mask:0xf
	v_add_f32_dpp v187, v187, v187 row_ror:1 row_mask:0xf bank_mask:0xf
	v_add_f32_dpp v188, v188, v188 row_ror:1 row_mask:0xf bank_mask:0xf
	v_add_f32_dpp v189, v189, v189 row_ror:1 row_mask:0xf bank_mask:0xf
	v_mov_b32_e32 v190, v186
	v_mov_b32_e32 v191, v187
	v_mov_b32_e32 v192, v188
	v_mov_b32_e32 v193, v189
	s_nop 1
	v_permlane16_swap_b32_e32 v190, v186
	v_permlane16_swap_b32_e32 v191, v187
	v_permlane16_swap_b32_e32 v192, v188
	v_permlane16_swap_b32_e32 v193, v189
	v_add_f32_e32 v186, v186, v190
	v_add_f32_e32 v187, v187, v191
	v_add_f32_e32 v188, v188, v192
	v_add_f32_e32 v189, v189, v193
	v_mov_b32_e32 v190, v186
	v_mov_b32_e32 v191, v187
	v_mov_b32_e32 v192, v188
	v_mov_b32_e32 v193, v189
	s_nop 1
	v_permlane32_swap_b32_e32 v190, v186
	v_permlane32_swap_b32_e32 v191, v187
	v_permlane32_swap_b32_e32 v192, v188
	v_permlane32_swap_b32_e32 v193, v189
	v_add_f32_e32 v186, v186, v190
	v_add_f32_e32 v187, v187, v191
	v_add_f32_e32 v188, v188, v192
	v_add_f32_e32 v189, v189, v193
	v_fma_f32 v186, v186, s3, v167
	v_fma_f32 v187, v187, s3, v167
	v_fma_f32 v188, v188, s3, v167
	v_fma_f32 v189, v189, s3, v167
	v_rsq_f32_e32 v186, v186
	v_rsq_f32_e32 v187, v187
	v_rsq_f32_e32 v188, v188
	v_rsq_f32_e32 v189, v189
	s_nop 0
	v_mul_f32_e32 v70, v70, v186
	v_mul_f32_e32 v71, v71, v186
	v_mul_f32_e32 v72, v72, v186
	v_mul_f32_e32 v73, v73, v186
	v_mul_f32_e32 v74, v74, v186
	v_mul_f32_e32 v75, v75, v186
	v_mul_f32_e32 v76, v76, v186
	v_mul_f32_e32 v77, v77, v186
	v_mul_f32_e32 v78, v78, v186
	v_mul_f32_e32 v79, v79, v186
	v_mul_f32_e32 v80, v80, v186
	v_mul_f32_e32 v81, v81, v186
	v_mul_f32_e32 v82, v82, v186
	v_mul_f32_e32 v83, v83, v186
	v_mul_f32_e32 v84, v84, v186
	v_mul_f32_e32 v85, v85, v186
	v_fma_f32 v70, v70, v150, v170
	v_fma_f32 v71, v71, v151, v171
	v_fma_f32 v72, v72, v152, v172
	v_fma_f32 v73, v73, v153, v173
	v_fma_f32 v74, v74, v154, v174
	v_fma_f32 v75, v75, v155, v175
	v_fma_f32 v76, v76, v156, v176
	v_fma_f32 v77, v77, v157, v177
	v_fma_f32 v78, v78, v158, v178
	v_fma_f32 v79, v79, v159, v179
	v_fma_f32 v80, v80, v160, v180
	v_fma_f32 v81, v81, v161, v181
	v_fma_f32 v82, v82, v162, v182
	v_fma_f32 v83, v83, v163, v183
	v_fma_f32 v84, v84, v164, v184
	v_fma_f32 v85, v85, v165, v185
	v_cvt_pk_bf16_f32 v70, v70, v71
	v_cvt_pk_bf16_f32 v71, v72, v73
	v_cvt_pk_bf16_f32 v72, v74, v75
	v_cvt_pk_bf16_f32 v73, v76, v77
	v_cvt_pk_bf16_f32 v78, v78, v79
	v_cvt_pk_bf16_f32 v79, v80, v81
	v_cvt_pk_bf16_f32 v80, v82, v83
	v_cvt_pk_bf16_f32 v81, v84, v85
	ds_write_b64 v202, v[70:71] offset:0
	ds_write_b64 v202, v[72:73] offset:8
	ds_write_b64 v202, v[78:79] offset:1024
	ds_write_b64 v202, v[80:81] offset:1032
	v_mul_f32_e32 v86, v86, v187
	v_mul_f32_e32 v87, v87, v187
	v_mul_f32_e32 v88, v88, v187
	v_mul_f32_e32 v89, v89, v187
	v_mul_f32_e32 v90, v90, v187
	v_mul_f32_e32 v91, v91, v187
	v_mul_f32_e32 v92, v92, v187
	v_mul_f32_e32 v93, v93, v187
	v_mul_f32_e32 v94, v94, v187
	v_mul_f32_e32 v95, v95, v187
	v_mul_f32_e32 v96, v96, v187
	v_mul_f32_e32 v97, v97, v187
	v_mul_f32_e32 v98, v98, v187
	v_mul_f32_e32 v99, v99, v187
	v_mul_f32_e32 v100, v100, v187
	v_mul_f32_e32 v101, v101, v187
	v_fma_f32 v86, v86, v150, v170
	v_fma_f32 v87, v87, v151, v171
	v_fma_f32 v88, v88, v152, v172
	v_fma_f32 v89, v89, v153, v173
	v_fma_f32 v90, v90, v154, v174
	v_fma_f32 v91, v91, v155, v175
	v_fma_f32 v92, v92, v156, v176
	v_fma_f32 v93, v93, v157, v177
	v_fma_f32 v94, v94, v158, v178
	v_fma_f32 v95, v95, v159, v179
	v_fma_f32 v96, v96, v160, v180
	v_fma_f32 v97, v97, v161, v181
	v_fma_f32 v98, v98, v162, v182
	v_fma_f32 v99, v99, v163, v183
	v_fma_f32 v100, v100, v164, v184
	v_fma_f32 v101, v101, v165, v185
	v_cvt_pk_bf16_f32 v86, v86, v87
	v_cvt_pk_bf16_f32 v87, v88, v89
	v_cvt_pk_bf16_f32 v88, v90, v91
	v_cvt_pk_bf16_f32 v89, v92, v93
	v_cvt_pk_bf16_f32 v94, v94, v95
	v_cvt_pk_bf16_f32 v95, v96, v97
	v_cvt_pk_bf16_f32 v96, v98, v99
	v_cvt_pk_bf16_f32 v97, v100, v101
	ds_write_b64 v202, v[86:87] offset:2056
	ds_write_b64 v202, v[88:89] offset:2064
	ds_write_b64 v202, v[94:95] offset:3080
	ds_write_b64 v202, v[96:97] offset:3088
	v_mul_f32_e32 v102, v102, v188
	v_mul_f32_e32 v103, v103, v188
	v_mul_f32_e32 v104, v104, v188
	v_mul_f32_e32 v105, v105, v188
	v_mul_f32_e32 v106, v106, v188
	v_mul_f32_e32 v107, v107, v188
	v_mul_f32_e32 v108, v108, v188
	v_mul_f32_e32 v109, v109, v188
	v_mul_f32_e32 v110, v110, v188
	v_mul_f32_e32 v111, v111, v188
	v_mul_f32_e32 v112, v112, v188
	v_mul_f32_e32 v113, v113, v188
	v_mul_f32_e32 v114, v114, v188
	v_mul_f32_e32 v115, v115, v188
	v_mul_f32_e32 v116, v116, v188
	v_mul_f32_e32 v117, v117, v188
	v_fma_f32 v102, v102, v150, v170
	v_fma_f32 v103, v103, v151, v171
	v_fma_f32 v104, v104, v152, v172
	v_fma_f32 v105, v105, v153, v173
	v_fma_f32 v106, v106, v154, v174
	v_fma_f32 v107, v107, v155, v175
	v_fma_f32 v108, v108, v156, v176
	v_fma_f32 v109, v109, v157, v177
	v_fma_f32 v110, v110, v158, v178
	v_fma_f32 v111, v111, v159, v179
	v_fma_f32 v112, v112, v160, v180
	v_fma_f32 v113, v113, v161, v181
	v_fma_f32 v114, v114, v162, v182
	v_fma_f32 v115, v115, v163, v183
	v_fma_f32 v116, v116, v164, v184
	v_fma_f32 v117, v117, v165, v185
	v_cvt_pk_bf16_f32 v102, v102, v103
	v_cvt_pk_bf16_f32 v103, v104, v105
	v_cvt_pk_bf16_f32 v104, v106, v107
	v_cvt_pk_bf16_f32 v105, v108, v109
	v_cvt_pk_bf16_f32 v110, v110, v111
	v_cvt_pk_bf16_f32 v111, v112, v113
	v_cvt_pk_bf16_f32 v112, v114, v115
	v_cvt_pk_bf16_f32 v113, v116, v117
	ds_write_b64 v202, v[102:103] offset:4112
	ds_write_b64 v202, v[104:105] offset:4120
	ds_write_b64 v202, v[110:111] offset:5136
	ds_write_b64 v202, v[112:113] offset:5144
	v_mul_f32_e32 v118, v118, v189
	v_mul_f32_e32 v119, v119, v189
	v_mul_f32_e32 v120, v120, v189
	v_mul_f32_e32 v121, v121, v189
	v_mul_f32_e32 v122, v122, v189
	v_mul_f32_e32 v123, v123, v189
	v_mul_f32_e32 v124, v124, v189
	v_mul_f32_e32 v125, v125, v189
	v_mul_f32_e32 v126, v126, v189
	v_mul_f32_e32 v127, v127, v189
	v_mul_f32_e32 v128, v128, v189
	v_mul_f32_e32 v129, v129, v189
	v_mul_f32_e32 v130, v130, v189
	v_mul_f32_e32 v131, v131, v189
	v_mul_f32_e32 v132, v132, v189
	v_mul_f32_e32 v133, v133, v189
	v_fma_f32 v118, v118, v150, v170
	v_fma_f32 v119, v119, v151, v171
	v_fma_f32 v120, v120, v152, v172
	v_fma_f32 v121, v121, v153, v173
	v_fma_f32 v122, v122, v154, v174
	v_fma_f32 v123, v123, v155, v175
	v_fma_f32 v124, v124, v156, v176
	v_fma_f32 v125, v125, v157, v177
	v_fma_f32 v126, v126, v158, v178
	v_fma_f32 v127, v127, v159, v179
	v_fma_f32 v128, v128, v160, v180
	v_fma_f32 v129, v129, v161, v181
	v_fma_f32 v130, v130, v162, v182
	v_fma_f32 v131, v131, v163, v183
	v_fma_f32 v132, v132, v164, v184
	v_fma_f32 v133, v133, v165, v185
	v_cvt_pk_bf16_f32 v118, v118, v119
	v_cvt_pk_bf16_f32 v119, v120, v121
	v_cvt_pk_bf16_f32 v120, v122, v123
	v_cvt_pk_bf16_f32 v121, v124, v125
	v_cvt_pk_bf16_f32 v126, v126, v127
	v_cvt_pk_bf16_f32 v127, v128, v129
	v_cvt_pk_bf16_f32 v128, v130, v131
	v_cvt_pk_bf16_f32 v129, v132, v133
	ds_write_b64 v202, v[118:119] offset:6168
	ds_write_b64 v202, v[120:121] offset:6176
	ds_write_b64 v202, v[126:127] offset:7192
	ds_write_b64 v202, v[128:129] offset:7200
	global_load_dwordx4 v[70:73], v201, s[10:11] offset:0
	global_load_dwordx4 v[74:77], v201, s[10:11] offset:16
	global_load_dwordx4 v[78:81], v201, s[10:11] offset:2048
	global_load_dwordx4 v[82:85], v201, s[10:11] offset:2064
	s_add_u32 s10, s10, 0x1000
	s_addc_u32 s11, s11, 0
	global_load_dwordx4 v[86:89], v201, s[10:11] offset:0
	global_load_dwordx4 v[90:93], v201, s[10:11] offset:16
	global_load_dwordx4 v[94:97], v201, s[10:11] offset:2048
	global_load_dwordx4 v[98:101], v201, s[10:11] offset:2064
	s_add_u32 s10, s10, 0x1000
	s_addc_u32 s11, s11, 0
	global_load_dwordx4 v[102:105], v201, s[10:11] offset:0
	global_load_dwordx4 v[106:109], v201, s[10:11] offset:16
	global_load_dwordx4 v[110:113], v201, s[10:11] offset:2048
	global_load_dwordx4 v[114:117], v201, s[10:11] offset:2064
	s_add_u32 s10, s10, 0x1000
	s_addc_u32 s11, s11, 0
	global_load_dwordx4 v[118:121], v201, s[10:11] offset:0
	global_load_dwordx4 v[122:125], v201, s[10:11] offset:16
	global_load_dwordx4 v[126:129], v201, s[10:11] offset:2048
	global_load_dwordx4 v[130:133], v201, s[10:11] offset:2064
	s_add_u32 s10, s10, 0x1000
	s_addc_u32 s11, s11, 0
	s_waitcnt vmcnt(12)
	v_mul_f32_e32 v186, v70, v70
	v_fmac_f32_e32 v186, v71, v71
	v_fmac_f32_e32 v186, v72, v72
	v_fmac_f32_e32 v186, v73, v73
	v_fmac_f32_e32 v186, v74, v74
	v_fmac_f32_e32 v186, v75, v75
	v_fmac_f32_e32 v186, v76, v76
	v_fmac_f32_e32 v186, v77, v77
	v_fmac_f32_e32 v186, v78, v78
	v_fmac_f32_e32 v186, v79, v79
	v_fmac_f32_e32 v186, v80, v80
	v_fmac_f32_e32 v186, v81, v81
	v_fmac_f32_e32 v186, v82, v82
	v_fmac_f32_e32 v186, v83, v83
	v_fmac_f32_e32 v186, v84, v84
	v_fmac_f32_e32 v186, v85, v85
	s_waitcnt vmcnt(8)
	v_mul_f32_e32 v187, v86, v86
	v_fmac_f32_e32 v187, v87, v87
	v_fmac_f32_e32 v187, v88, v88
	v_fmac_f32_e32 v187, v89, v89
	v_fmac_f32_e32 v187, v90, v90
	v_fmac_f32_e32 v187, v91, v91
	v_fmac_f32_e32 v187, v92, v92
	v_fmac_f32_e32 v187, v93, v93
	v_fmac_f32_e32 v187, v94, v94
	v_fmac_f32_e32 v187, v95, v95
	v_fmac_f32_e32 v187, v96, v96
	v_fmac_f32_e32 v187, v97, v97
	v_fmac_f32_e32 v187, v98, v98
	v_fmac_f32_e32 v187, v99, v99
	v_fmac_f32_e32 v187, v100, v100
	v_fmac_f32_e32 v187, v101, v101
	s_waitcnt vmcnt(4)
	v_mul_f32_e32 v188, v102, v102
	v_fmac_f32_e32 v188, v103, v103
	v_fmac_f32_e32 v188, v104, v104
	v_fmac_f32_e32 v188, v105, v105
	v_fmac_f32_e32 v188, v106, v106
	v_fmac_f32_e32 v188, v107, v107
	v_fmac_f32_e32 v188, v108, v108
	v_fmac_f32_e32 v188, v109, v109
	v_fmac_f32_e32 v188, v110, v110
	v_fmac_f32_e32 v188, v111, v111
	v_fmac_f32_e32 v188, v112, v112
	v_fmac_f32_e32 v188, v113, v113
	v_fmac_f32_e32 v188, v114, v114
	v_fmac_f32_e32 v188, v115, v115
	v_fmac_f32_e32 v188, v116, v116
	v_fmac_f32_e32 v188, v117, v117
	s_waitcnt vmcnt(0)
	v_mul_f32_e32 v189, v118, v118
	v_fmac_f32_e32 v189, v119, v119
	v_fmac_f32_e32 v189, v120, v120
	v_fmac_f32_e32 v189, v121, v121
	v_fmac_f32_e32 v189, v122, v122
	v_fmac_f32_e32 v189, v123, v123
	v_fmac_f32_e32 v189, v124, v124
	v_fmac_f32_e32 v189, v125, v125
	v_fmac_f32_e32 v189, v126, v126
	v_fmac_f32_e32 v189, v127, v127
	v_fmac_f32_e32 v189, v128, v128
	v_fmac_f32_e32 v189, v129, v129
	v_fmac_f32_e32 v189, v130, v130
	v_fmac_f32_e32 v189, v131, v131
	v_fmac_f32_e32 v189, v132, v132
	v_fmac_f32_e32 v189, v133, v133
	s_nop 1
	v_add_f32_dpp v186, v186, v186 row_ror:8 row_mask:0xf bank_mask:0xf
	v_add_f32_dpp v187, v187, v187 row_ror:8 row_mask:0xf bank_mask:0xf
	v_add_f32_dpp v188, v188, v188 row_ror:8 row_mask:0xf bank_mask:0xf
	v_add_f32_dpp v189, v189, v189 row_ror:8 row_mask:0xf bank_mask:0xf
	v_add_f32_dpp v186, v186, v186 row_ror:4 row_mask:0xf bank_mask:0xf
	v_add_f32_dpp v187, v187, v187 row_ror:4 row_mask:0xf bank_mask:0xf
	v_add_f32_dpp v188, v188, v188 row_ror:4 row_mask:0xf bank_mask:0xf
	v_add_f32_dpp v189, v189, v189 row_ror:4 row_mask:0xf bank_mask:0xf
	v_add_f32_dpp v186, v186, v186 row_ror:2 row_mask:0xf bank_mask:0xf
	v_add_f32_dpp v187, v187, v187 row_ror:2 row_mask:0xf bank_mask:0xf
	v_add_f32_dpp v188, v188, v188 row_ror:2 row_mask:0xf bank_mask:0xf
	v_add_f32_dpp v189, v189, v189 row_ror:2 row_mask:0xf bank_mask:0xf
	v_add_f32_dpp v186, v186, v186 row_ror:1 row_mask:0xf bank_mask:0xf
	v_add_f32_dpp v187, v187, v187 row_ror:1 row_mask:0xf bank_mask:0xf
	v_add_f32_dpp v188, v188, v188 row_ror:1 row_mask:0xf bank_mask:0xf
	v_add_f32_dpp v189, v189, v189 row_ror:1 row_mask:0xf bank_mask:0xf
	v_mov_b32_e32 v190, v186
	v_mov_b32_e32 v191, v187
	v_mov_b32_e32 v192, v188
	v_mov_b32_e32 v193, v189
	s_nop 1
	v_permlane16_swap_b32_e32 v190, v186
	v_permlane16_swap_b32_e32 v191, v187
	v_permlane16_swap_b32_e32 v192, v188
	v_permlane16_swap_b32_e32 v193, v189
	v_add_f32_e32 v186, v186, v190
	v_add_f32_e32 v187, v187, v191
	v_add_f32_e32 v188, v188, v192
	v_add_f32_e32 v189, v189, v193
	v_mov_b32_e32 v190, v186
	v_mov_b32_e32 v191, v187
	v_mov_b32_e32 v192, v188
	v_mov_b32_e32 v193, v189
	s_nop 1
	v_permlane32_swap_b32_e32 v190, v186
	v_permlane32_swap_b32_e32 v191, v187
	v_permlane32_swap_b32_e32 v192, v188
	v_permlane32_swap_b32_e32 v193, v189
	v_add_f32_e32 v186, v186, v190
	v_add_f32_e32 v187, v187, v191
	v_add_f32_e32 v188, v188, v192
	v_add_f32_e32 v189, v189, v193
	v_fma_f32 v186, v186, s3, v167
	v_fma_f32 v187, v187, s3, v167
	v_fma_f32 v188, v188, s3, v167
	v_fma_f32 v189, v189, s3, v167
	v_rsq_f32_e32 v186, v186
	v_rsq_f32_e32 v187, v187
	v_rsq_f32_e32 v188, v188
	v_rsq_f32_e32 v189, v189
	s_nop 0
	v_mul_f32_e32 v70, v70, v186
	v_mul_f32_e32 v71, v71, v186
	v_mul_f32_e32 v72, v72, v186
	v_mul_f32_e32 v73, v73, v186
	v_mul_f32_e32 v74, v74, v186
	v_mul_f32_e32 v75, v75, v186
	v_mul_f32_e32 v76, v76, v186
	v_mul_f32_e32 v77, v77, v186
	v_mul_f32_e32 v78, v78, v186
	v_mul_f32_e32 v79, v79, v186
	v_mul_f32_e32 v80, v80, v186
	v_mul_f32_e32 v81, v81, v186
	v_mul_f32_e32 v82, v82, v186
	v_mul_f32_e32 v83, v83, v186
	v_mul_f32_e32 v84, v84, v186
	v_mul_f32_e32 v85, v85, v186
	v_fma_f32 v70, v70, v150, v170
	v_fma_f32 v71, v71, v151, v171
	v_fma_f32 v72, v72, v152, v172
	v_fma_f32 v73, v73, v153, v173
	v_fma_f32 v74, v74, v154, v174
	v_fma_f32 v75, v75, v155, v175
	v_fma_f32 v76, v76, v156, v176
	v_fma_f32 v77, v77, v157, v177
	v_fma_f32 v78, v78, v158, v178
	v_fma_f32 v79, v79, v159, v179
	v_fma_f32 v80, v80, v160, v180
	v_fma_f32 v81, v81, v161, v181
	v_fma_f32 v82, v82, v162, v182
	v_fma_f32 v83, v83, v163, v183
	v_fma_f32 v84, v84, v164, v184
	v_fma_f32 v85, v85, v165, v185
	v_cvt_pk_bf16_f32 v70, v70, v71
	v_cvt_pk_bf16_f32 v71, v72, v73
	v_cvt_pk_bf16_f32 v72, v74, v75
	v_cvt_pk_bf16_f32 v73, v76, v77
	v_cvt_pk_bf16_f32 v78, v78, v79
	v_cvt_pk_bf16_f32 v79, v80, v81
	v_cvt_pk_bf16_f32 v80, v82, v83
	v_cvt_pk_bf16_f32 v81, v84, v85
	ds_write_b64 v202, v[70:71] offset:8224
	ds_write_b64 v202, v[72:73] offset:8232
	ds_write_b64 v202, v[78:79] offset:9248
	ds_write_b64 v202, v[80:81] offset:9256
	v_mul_f32_e32 v86, v86, v187
	v_mul_f32_e32 v87, v87, v187
	v_mul_f32_e32 v88, v88, v187
	v_mul_f32_e32 v89, v89, v187
	v_mul_f32_e32 v90, v90, v187
	v_mul_f32_e32 v91, v91, v187
	v_mul_f32_e32 v92, v92, v187
	v_mul_f32_e32 v93, v93, v187
	v_mul_f32_e32 v94, v94, v187
	v_mul_f32_e32 v95, v95, v187
	v_mul_f32_e32 v96, v96, v187
	v_mul_f32_e32 v97, v97, v187
	v_mul_f32_e32 v98, v98, v187
	v_mul_f32_e32 v99, v99, v187
	v_mul_f32_e32 v100, v100, v187
	v_mul_f32_e32 v101, v101, v187
	v_fma_f32 v86, v86, v150, v170
	v_fma_f32 v87, v87, v151, v171
	v_fma_f32 v88, v88, v152, v172
	v_fma_f32 v89, v89, v153, v173
	v_fma_f32 v90, v90, v154, v174
	v_fma_f32 v91, v91, v155, v175
	v_fma_f32 v92, v92, v156, v176
	v_fma_f32 v93, v93, v157, v177
	v_fma_f32 v94, v94, v158, v178
	v_fma_f32 v95, v95, v159, v179
	v_fma_f32 v96, v96, v160, v180
	v_fma_f32 v97, v97, v161, v181
	v_fma_f32 v98, v98, v162, v182
	v_fma_f32 v99, v99, v163, v183
	v_fma_f32 v100, v100, v164, v184
	v_fma_f32 v101, v101, v165, v185
	v_cvt_pk_bf16_f32 v86, v86, v87
	v_cvt_pk_bf16_f32 v87, v88, v89
	v_cvt_pk_bf16_f32 v88, v90, v91
	v_cvt_pk_bf16_f32 v89, v92, v93
	v_cvt_pk_bf16_f32 v94, v94, v95
	v_cvt_pk_bf16_f32 v95, v96, v97
	v_cvt_pk_bf16_f32 v96, v98, v99
	v_cvt_pk_bf16_f32 v97, v100, v101
	ds_write_b64 v202, v[86:87] offset:10280
	ds_write_b64 v202, v[88:89] offset:10288
	ds_write_b64 v202, v[94:95] offset:11304
	ds_write_b64 v202, v[96:97] offset:11312
	v_mul_f32_e32 v102, v102, v188
	v_mul_f32_e32 v103, v103, v188
	v_mul_f32_e32 v104, v104, v188
	v_mul_f32_e32 v105, v105, v188
	v_mul_f32_e32 v106, v106, v188
	v_mul_f32_e32 v107, v107, v188
	v_mul_f32_e32 v108, v108, v188
	v_mul_f32_e32 v109, v109, v188
	v_mul_f32_e32 v110, v110, v188
	v_mul_f32_e32 v111, v111, v188
	v_mul_f32_e32 v112, v112, v188
	v_mul_f32_e32 v113, v113, v188
	v_mul_f32_e32 v114, v114, v188
	v_mul_f32_e32 v115, v115, v188
	v_mul_f32_e32 v116, v116, v188
	v_mul_f32_e32 v117, v117, v188
	v_fma_f32 v102, v102, v150, v170
	v_fma_f32 v103, v103, v151, v171
	v_fma_f32 v104, v104, v152, v172
	v_fma_f32 v105, v105, v153, v173
	v_fma_f32 v106, v106, v154, v174
	v_fma_f32 v107, v107, v155, v175
	v_fma_f32 v108, v108, v156, v176
	v_fma_f32 v109, v109, v157, v177
	v_fma_f32 v110, v110, v158, v178
	v_fma_f32 v111, v111, v159, v179
	v_fma_f32 v112, v112, v160, v180
	v_fma_f32 v113, v113, v161, v181
	v_fma_f32 v114, v114, v162, v182
	v_fma_f32 v115, v115, v163, v183
	v_fma_f32 v116, v116, v164, v184
	v_fma_f32 v117, v117, v165, v185
	v_cvt_pk_bf16_f32 v102, v102, v103
	v_cvt_pk_bf16_f32 v103, v104, v105
	v_cvt_pk_bf16_f32 v104, v106, v107
	v_cvt_pk_bf16_f32 v105, v108, v109
	v_cvt_pk_bf16_f32 v110, v110, v111
	v_cvt_pk_bf16_f32 v111, v112, v113
	v_cvt_pk_bf16_f32 v112, v114, v115
	v_cvt_pk_bf16_f32 v113, v116, v117
	ds_write_b64 v202, v[102:103] offset:12336
	ds_write_b64 v202, v[104:105] offset:12344
	ds_write_b64 v202, v[110:111] offset:13360
	ds_write_b64 v202, v[112:113] offset:13368
	v_mul_f32_e32 v118, v118, v189
	v_mul_f32_e32 v119, v119, v189
	v_mul_f32_e32 v120, v120, v189
	v_mul_f32_e32 v121, v121, v189
	v_mul_f32_e32 v122, v122, v189
	v_mul_f32_e32 v123, v123, v189
	v_mul_f32_e32 v124, v124, v189
	v_mul_f32_e32 v125, v125, v189
	v_mul_f32_e32 v126, v126, v189
	v_mul_f32_e32 v127, v127, v189
	v_mul_f32_e32 v128, v128, v189
	v_mul_f32_e32 v129, v129, v189
	v_mul_f32_e32 v130, v130, v189
	v_mul_f32_e32 v131, v131, v189
	v_mul_f32_e32 v132, v132, v189
	v_mul_f32_e32 v133, v133, v189
	v_fma_f32 v118, v118, v150, v170
	v_fma_f32 v119, v119, v151, v171
	v_fma_f32 v120, v120, v152, v172
	v_fma_f32 v121, v121, v153, v173
	v_fma_f32 v122, v122, v154, v174
	v_fma_f32 v123, v123, v155, v175
	v_fma_f32 v124, v124, v156, v176
	v_fma_f32 v125, v125, v157, v177
	v_fma_f32 v126, v126, v158, v178
	v_fma_f32 v127, v127, v159, v179
	v_fma_f32 v128, v128, v160, v180
	v_fma_f32 v129, v129, v161, v181
	v_fma_f32 v130, v130, v162, v182
	v_fma_f32 v131, v131, v163, v183
	v_fma_f32 v132, v132, v164, v184
	v_fma_f32 v133, v133, v165, v185
	v_cvt_pk_bf16_f32 v118, v118, v119
	v_cvt_pk_bf16_f32 v119, v120, v121
	v_cvt_pk_bf16_f32 v120, v122, v123
	v_cvt_pk_bf16_f32 v121, v124, v125
	v_cvt_pk_bf16_f32 v126, v126, v127
	v_cvt_pk_bf16_f32 v127, v128, v129
	v_cvt_pk_bf16_f32 v128, v130, v131
	v_cvt_pk_bf16_f32 v129, v132, v133
	ds_write_b64 v202, v[118:119] offset:14392
	ds_write_b64 v202, v[120:121] offset:14400
	ds_write_b64 v202, v[126:127] offset:15416
	ds_write_b64 v202, v[128:129] offset:15424
	s_waitcnt lgkmcnt(0)
	s_barrier
	v_mbcnt_lo_u32_b32 v91, -1, 0
	v_mbcnt_hi_u32_b32 v91, -1, v91
	v_readlane_b32 s9, v254, 63
	v_and_b32_e32 v88, 7, v91
	v_lshrrev_b32_e32 v89, 3, v91
	v_lshl_add_u32 v89, s9, 3, v89
	v_mul_u32_u24_e32 v90, 16448, v88
	v_lshl_add_u32 v90, v89, 2, v90
	v_mul_u32_u24_e32 v89, 0xc000, v89
	v_lshl_add_u32 v89, v88, 4, v89
	v_add_u32_e32 v88, 0x6000, v89
	s_lshl_b32 s8, s7, 7
	v_readlane_b32 s10, v255, 7
	v_readlane_b32 s11, v255, 8
	s_add_u32 s10, s10, 0xd000000
	s_addc_u32 s11, s11, 0
	s_add_u32 s10, s10, s8
	s_addc_u32 s11, s11, 0
	s_mov_b32 s1, 0x5040100
	s_mov_b32 s3, 0x7060302
	ds_read_b32 v70, v90 offset:0
	ds_read_b32 v71, v90 offset:2056
	ds_read_b32 v72, v90 offset:4112
	ds_read_b32 v73, v90 offset:6168
	ds_read_b32 v74, v90 offset:8224
	ds_read_b32 v75, v90 offset:10280
	ds_read_b32 v76, v90 offset:12336
	ds_read_b32 v77, v90 offset:14392
	ds_read_b32 v92, v90 offset:256
	ds_read_b32 v93, v90 offset:2312
	ds_read_b32 v94, v90 offset:4368
	ds_read_b32 v95, v90 offset:6424
	ds_read_b32 v96, v90 offset:8480
	ds_read_b32 v97, v90 offset:10536
	ds_read_b32 v98, v90 offset:12592
	ds_read_b32 v99, v90 offset:14648
	s_waitcnt lgkmcnt(8)
	v_perm_b32 v80, v71, v70, s1
	v_perm_b32 v81, v73, v72, s1
	v_perm_b32 v82, v75, v74, s1
	v_perm_b32 v83, v77, v76, s1
	v_perm_b32 v84, v71, v70, s3
	v_perm_b32 v85, v73, v72, s3
	v_perm_b32 v86, v75, v74, s3
	v_perm_b32 v87, v77, v76, s3
	global_store_dwordx4 v89, v[80:83], s[10:11]
	global_store_dwordx4 v88, v[84:87], s[10:11]
	s_add_u32 s10, s10, 0x300000
	s_addc_u32 s11, s11, 0
	ds_read_b32 v70, v90 offset:512
	ds_read_b32 v71, v90 offset:2568
	ds_read_b32 v72, v90 offset:4624
	ds_read_b32 v73, v90 offset:6680
	ds_read_b32 v74, v90 offset:8736
	ds_read_b32 v75, v90 offset:10792
	ds_read_b32 v76, v90 offset:12848
	ds_read_b32 v77, v90 offset:14904
	s_waitcnt lgkmcnt(8)
	v_perm_b32 v80, v93, v92, s1
	v_perm_b32 v81, v95, v94, s1
	v_perm_b32 v82, v97, v96, s1
	v_perm_b32 v83, v99, v98, s1
	v_perm_b32 v84, v93, v92, s3
	v_perm_b32 v85, v95, v94, s3
	v_perm_b32 v86, v97, v96, s3
	v_perm_b32 v87, v99, v98, s3
	global_store_dwordx4 v89, v[80:83], s[10:11]
	global_store_dwordx4 v88, v[84:87], s[10:11]
	s_add_u32 s10, s10, 0x300000
	s_addc_u32 s11, s11, 0
	ds_read_b32 v92, v90 offset:768
	ds_read_b32 v93, v90 offset:2824
	ds_read_b32 v94, v90 offset:4880
	ds_read_b32 v95, v90 offset:6936
	ds_read_b32 v96, v90 offset:8992
	ds_read_b32 v97, v90 offset:11048
	ds_read_b32 v98, v90 offset:13104
	ds_read_b32 v99, v90 offset:15160
	s_waitcnt lgkmcnt(8)
	v_perm_b32 v80, v71, v70, s1
	v_perm_b32 v81, v73, v72, s1
	v_perm_b32 v82, v75, v74, s1
	v_perm_b32 v83, v77, v76, s1
	v_perm_b32 v84, v71, v70, s3
	v_perm_b32 v85, v73, v72, s3
	v_perm_b32 v86, v75, v74, s3
	v_perm_b32 v87, v77, v76, s3
	global_store_dwordx4 v89, v[80:83], s[10:11]
	global_store_dwordx4 v88, v[84:87], s[10:11]
	s_add_u32 s10, s10, 0x300000
	s_addc_u32 s11, s11, 0
	ds_read_b32 v70, v90 offset:1024
	ds_read_b32 v71, v90 offset:3080
	ds_read_b32 v72, v90 offset:5136
	ds_read_b32 v73, v90 offset:7192
	ds_read_b32 v74, v90 offset:9248
	ds_read_b32 v75, v90 offset:11304
	ds_read_b32 v76, v90 offset:13360
	ds_read_b32 v77, v90 offset:15416
	s_waitcnt lgkmcnt(8)
	v_perm_b32 v80, v93, v92, s1
	v_perm_b32 v81, v95, v94, s1
	v_perm_b32 v82, v97, v96, s1
	v_perm_b32 v83, v99, v98, s1
	v_perm_b32 v84, v93, v92, s3
	v_perm_b32 v85, v95, v94, s3
	v_perm_b32 v86, v97, v96, s3
	v_perm_b32 v87, v99, v98, s3
	global_store_dwordx4 v89, v[80:83], s[10:11]
	global_store_dwordx4 v88, v[84:87], s[10:11]
	s_add_u32 s10, s10, 0x300000
	s_addc_u32 s11, s11, 0
	ds_read_b32 v92, v90 offset:1280
	ds_read_b32 v93, v90 offset:3336
	ds_read_b32 v94, v90 offset:5392
	ds_read_b32 v95, v90 offset:7448
	ds_read_b32 v96, v90 offset:9504
	ds_read_b32 v97, v90 offset:11560
	ds_read_b32 v98, v90 offset:13616
	ds_read_b32 v99, v90 offset:15672
	s_waitcnt lgkmcnt(8)
	v_perm_b32 v80, v71, v70, s1
	v_perm_b32 v81, v73, v72, s1
	v_perm_b32 v82, v75, v74, s1
	v_perm_b32 v83, v77, v76, s1
	v_perm_b32 v84, v71, v70, s3
	v_perm_b32 v85, v73, v72, s3
	v_perm_b32 v86, v75, v74, s3
	v_perm_b32 v87, v77, v76, s3
	global_store_dwordx4 v89, v[80:83], s[10:11]
	global_store_dwordx4 v88, v[84:87], s[10:11]
	s_add_u32 s10, s10, 0x300000
	s_addc_u32 s11, s11, 0
	ds_read_b32 v70, v90 offset:1536
	ds_read_b32 v71, v90 offset:3592
	ds_read_b32 v72, v90 offset:5648
	ds_read_b32 v73, v90 offset:7704
	ds_read_b32 v74, v90 offset:9760
	ds_read_b32 v75, v90 offset:11816
	ds_read_b32 v76, v90 offset:13872
	ds_read_b32 v77, v90 offset:15928
	s_waitcnt lgkmcnt(8)
	v_perm_b32 v80, v93, v92, s1
	v_perm_b32 v81, v95, v94, s1
	v_perm_b32 v82, v97, v96, s1
	v_perm_b32 v83, v99, v98, s1
	v_perm_b32 v84, v93, v92, s3
	v_perm_b32 v85, v95, v94, s3
	v_perm_b32 v86, v97, v96, s3
	v_perm_b32 v87, v99, v98, s3
	global_store_dwordx4 v89, v[80:83], s[10:11]
	global_store_dwordx4 v88, v[84:87], s[10:11]
	s_add_u32 s10, s10, 0x300000
	s_addc_u32 s11, s11, 0
	ds_read_b32 v92, v90 offset:1792
	ds_read_b32 v93, v90 offset:3848
	ds_read_b32 v94, v90 offset:5904
	ds_read_b32 v95, v90 offset:7960
	ds_read_b32 v96, v90 offset:10016
	ds_read_b32 v97, v90 offset:12072
	ds_read_b32 v98, v90 offset:14128
	ds_read_b32 v99, v90 offset:16184
	s_waitcnt lgkmcnt(8)
	v_perm_b32 v80, v71, v70, s1
	v_perm_b32 v81, v73, v72, s1
	v_perm_b32 v82, v75, v74, s1
	v_perm_b32 v83, v77, v76, s1
	v_perm_b32 v84, v71, v70, s3
	v_perm_b32 v85, v73, v72, s3
	v_perm_b32 v86, v75, v74, s3
	v_perm_b32 v87, v77, v76, s3
	global_store_dwordx4 v89, v[80:83], s[10:11]
	global_store_dwordx4 v88, v[84:87], s[10:11]
	s_add_u32 s10, s10, 0x300000
	s_addc_u32 s11, s11, 0
	s_waitcnt lgkmcnt(0)
	v_perm_b32 v80, v93, v92, s1
	v_perm_b32 v81, v95, v94, s1
	v_perm_b32 v82, v97, v96, s1
	v_perm_b32 v83, v99, v98, s1
	v_perm_b32 v84, v93, v92, s3
	v_perm_b32 v85, v95, v94, s3
	v_perm_b32 v86, v97, v96, s3
	v_perm_b32 v87, v99, v98, s3
	global_store_dwordx4 v89, v[80:83], s[10:11]
	global_store_dwordx4 v88, v[84:87], s[10:11]
	s_add_i32 s7, s7, s78
	s_add_i32 s2, s2, s35
	s_cmpk_gt_i32 s7, 0xbf
	s_barrier
	s_cbranch_scc0 .LBB0_896
